# phase-1 Q/K epilogue: tile row scales staged once in LDS and read by ds_read (no per-group vmcnt waits that drained the scattered stores), on top of v_pletouch
# baseline (speedup 1.0000x reference)
.LBB0_212:
	s_bfe_u32 s1, s0, 0x20008
	v_cvt_f32_ubyte0_e32 v130, s1
	v_sub_f32_e32 v130, 0xc0a00000, v130
	v_cmp_gt_f32_e32 vcc, s43, v130
	s_and_b32 s0, s0, 0x80
	s_and_b64 s[4:5], vcc, exec
	v_cndmask_b32_e32 v131, 0, v169, vcc
	v_add_f32_e32 v130, v130, v131
	v_exp_f32_e32 v130, v130
	s_cselect_b32 s4, 0xffffffc0, 0
	v_lshlrev_b64 v[128:129], 2, v[128:129]
	v_or_b32_e32 v128, s1, v128
	v_ldexp_f32 v133, v130, s4
	v_sub_f32_e32 v144, 1.0, v133
	v_add_f32_e32 v130, -1.0, v144
	v_sub_f32_e32 v131, v130, v144
	v_add_f32_e32 v131, 1.0, v131
	v_sub_f32_e64 v130, -v133, v130
	v_add_f32_e32 v145, v130, v131
	v_frexp_mant_f32_e32 v152, v144
	v_cvt_f64_f32_e32 v[130:131], v144
	v_frexp_exp_i32_f64_e32 v130, v[130:131]
	v_cmp_gt_f32_e32 vcc, s44, v152
	s_cmp_gt_u32 s26, 7
	s_mov_b64 s[4:5], -1
	v_subbrev_co_u32_e32 v152, vcc, 0, v130, vcc
	v_sub_u32_e32 v130, 0, v152
	v_ldexp_f32 v131, v144, v130
	v_add_f32_e32 v144, -1.0, v131
	v_add_f32_e32 v155, 1.0, v131
	v_ldexp_f32 v130, v145, v130
	v_add_f32_e32 v145, 1.0, v144
	v_add_f32_e32 v156, -1.0, v155
	v_sub_f32_e32 v145, v131, v145
	v_sub_f32_e32 v131, v131, v156
	v_add_f32_e32 v145, v130, v145
	v_add_f32_e32 v130, v130, v131
	v_add_f32_e32 v131, v155, v130
	v_rcp_f32_e32 v156, v131
	v_add_f32_e32 v154, v144, v145
	v_sub_f32_e32 v144, v154, v144
	v_sub_f32_e32 v144, v145, v144
	v_sub_f32_e32 v145, v131, v155
	v_sub_f32_e32 v130, v130, v145
	v_mul_f32_e32 v145, v154, v156
	v_mul_f32_e32 v155, v131, v145
	v_fma_f32 v157, v145, v131, -v155
	v_fmac_f32_e32 v157, v145, v130
	v_add_f32_e32 v161, v155, v157
	v_sub_f32_e32 v162, v154, v161
	v_sub_f32_e32 v154, v154, v162
	v_sub_f32_e32 v155, v161, v155
	v_sub_f32_e32 v154, v154, v161
	v_add_f32_e32 v144, v144, v154
	v_sub_f32_e32 v154, v155, v157
	v_add_f32_e32 v144, v154, v144
	v_add_f32_e32 v154, v162, v144
	v_mul_f32_e32 v155, v156, v154
	v_mul_f32_e32 v157, v131, v155
	v_fma_f32 v131, v155, v131, -v157
	v_fmac_f32_e32 v131, v155, v130
	v_sub_f32_e32 v130, v162, v154
	v_add_f32_e32 v130, v144, v130
	v_add_f32_e32 v144, v157, v131
	v_sub_f32_e32 v161, v154, v144
	v_sub_f32_e32 v154, v154, v161
	v_sub_f32_e32 v157, v144, v157
	v_sub_f32_e32 v144, v154, v144
	v_add_f32_e32 v130, v130, v144
	v_sub_f32_e32 v131, v157, v131
	v_add_f32_e32 v130, v131, v130
	v_add_f32_e32 v130, v161, v130
	v_mul_f32_e32 v144, v156, v130
	v_lshl_add_u64 v[130:131], v[136:137], 2, s[8:9]
	v_and_b32_e32 v180, 0xffffff00, v136
	v_add_u32_e32 v180, v180, v220
	v_mov_b32_e32 v181, 0
	v_lshl_add_u64 v[182:183], v[180:181], 2, s[8:9]
	global_load_dword v180, v[182:183], off
	v_lshlrev_b32_e32 v181, 2, v220
	v_subrev_u32_e32 v255, s8, v130
	v_and_b32_e32 v255, 0x3ff, v255
	v_add_u32_e32 v255, 0xc000, v255
	s_waitcnt vmcnt(0)
	ds_write_b32 v181, v180 offset:49152
	s_waitcnt lgkmcnt(0)
	s_barrier
	ds_read2_b32 v[180:181], v255 offset1:1
	ds_read2_b32 v[182:183], v255 offset0:2 offset1:3
	v_add_f32_e32 v154, v145, v155
	v_sub_f32_e32 v137, v154, v145
	v_cvt_f32_i32_e32 v145, v152
	v_sub_f32_e32 v137, v155, v137
	v_add_f32_e32 v137, v137, v144
	v_add_f32_e32 v144, v154, v137
	v_mul_f32_e32 v156, 0x3f317218, v145
	v_fma_f32 v157, v145, s45, -v156
	v_mul_f32_e32 v152, v144, v144
	v_mov_b32_e32 v155, 0x3ecc95a3
	v_fmac_f32_e32 v157, 0xb102e308, v145
	v_sub_f32_e32 v145, v144, v154
	v_fmamk_f32 v155, v152, 0x3e9b6dac, v155
	v_sub_f32_e32 v137, v137, v145
	v_add_f32_e32 v145, v156, v157
	v_fmaak_f32 v155, v152, v155, 0x3f2aaada
	v_sub_f32_e32 v154, v145, v156
	v_ldexp_f32 v156, v144, 1
	v_mul_f32_e32 v144, v144, v152
	v_mul_f32_e32 v144, v144, v155
	v_add_f32_e32 v152, v156, v144
	v_sub_f32_e32 v155, v152, v156
	v_ldexp_f32 v137, v137, 1
	v_sub_f32_e32 v144, v144, v155
	v_add_f32_e32 v137, v137, v144
	v_add_f32_e32 v144, v152, v137
	v_sub_f32_e32 v152, v144, v152
	v_sub_f32_e32 v137, v137, v152
	v_add_f32_e32 v152, v145, v144
	v_sub_f32_e32 v155, v152, v145
	v_sub_f32_e32 v156, v152, v155
	v_sub_f32_e32 v154, v157, v154
	v_sub_f32_e32 v145, v145, v156
	v_sub_f32_e32 v144, v144, v155
	v_add_f32_e32 v144, v144, v145
	v_add_f32_e32 v145, v154, v137
	v_sub_f32_e32 v155, v145, v154
	v_add_f32_e32 v144, v145, v144
	v_sub_f32_e32 v156, v145, v155
	v_add_f32_e32 v145, v152, v144
	v_sub_f32_e32 v154, v154, v156
	v_sub_f32_e32 v137, v137, v155
	v_sub_f32_e32 v152, v145, v152
	v_add_f32_e32 v137, v137, v154
	v_sub_f32_e32 v144, v144, v152
	v_add_f32_e32 v137, v137, v144
	v_add_f32_e32 v137, v145, v137
	v_mov_b32_e32 v144, 0x7fc00000
	v_cmp_nlt_f32_e32 vcc, 1.0, v133
	v_or_b32_e32 v154, s0, v160
	s_cselect_b64 s[0:1], -1, 0
	v_cndmask_b32_e32 v137, v144, v137, vcc
	v_mov_b32_e32 v144, 0xff800000
	v_cmp_neq_f32_e32 vcc, 1.0, v133
	v_or_b32_e32 v197, v154, v158
	v_or_b32_e32 v195, 16, v197
	v_cndmask_b32_e32 v137, v144, v137, vcc
	v_cmp_gt_f32_e32 vcc, s46, v133
	v_lshlrev_b64 v[144:145], 14, v[128:129]
	v_lshlrev_b64 v[128:129], 15, v[128:129]
	v_cndmask_b32_e64 v137, v137, -v133, vcc
	v_lshrrev_b32_e32 v133, 1, v154
	v_or_b32_e32 v133, v133, v158
	v_cvt_f32_ubyte0_e32 v133, v133
	v_mul_f32_e32 v152, 0xbdd49a78, v133
	v_cmp_gt_f32_e32 vcc, s43, v152
	s_waitcnt lgkmcnt(0)
	v_mul_f32_e32 v120, v120, v180
	v_cndmask_b32_e32 v152, 0, v169, vcc
	v_fmac_f32_e32 v152, 0xbdd49a78, v133
	v_exp_f32_e32 v133, v152
	v_and_b32_e32 v152, 0x3f8c, v136
	v_cvt_f32_u32_e32 v160, v152
	v_cndmask_b32_e32 v155, 0, v170, vcc
	v_ldexp_f32 v133, v133, v155
	v_mul_f32_e32 v218, 0.15915494, v133
	v_mul_f32_e32 v133, v218, v160
	v_fma_f32 v155, v160, v218, -v133
	v_floor_f32_e32 v133, v133
	v_fma_f32 v133, v218, v160, -v133
	v_add_f32_e32 v133, v155, v133
	v_sin_f32_e32 v156, v133
	v_or_b32_e32 v157, 1, v152
	v_cos_f32_e32 v133, v133
	v_cvt_f32_u32_e32 v165, v157
	v_mul_f32_e32 v124, v124, v180
	v_mul_f32_e32 v155, v156, v120
	v_fma_f32 v157, v133, v124, -v155
	v_mul_f32_e32 v155, v133, v120
	v_mul_f32_e32 v120, v218, v165
	v_fmac_f32_e32 v155, v156, v124
	v_fma_f32 v124, v165, v218, -v120
	v_floor_f32_e32 v120, v120
	v_fma_f32 v120, v218, v165, -v120
	v_add_f32_e32 v120, v124, v120
	v_sin_f32_e32 v124, v120
	v_or_b32_e32 v156, 2, v152
	v_cos_f32_e32 v120, v120
	v_cvt_f32_u32_e32 v178, v156
	v_mul_f32_e32 v121, v121, v181
	v_mul_f32_e32 v125, v125, v181
	v_mul_f32_e32 v133, v124, v121
	v_fma_f32 v163, v120, v125, -v133
	v_mul_f32_e32 v161, v120, v121
	v_mul_f32_e32 v120, v218, v178
	v_fma_f32 v121, v178, v218, -v120
	v_floor_f32_e32 v120, v120
	v_fma_f32 v120, v218, v178, -v120
	v_add_f32_e32 v120, v121, v120
	v_fmac_f32_e32 v161, v124, v125
	v_sin_f32_e32 v121, v120
	v_mul_f32_e32 v124, v126, v182
	v_or_b32_e32 v126, 3, v152
	v_cos_f32_e32 v120, v120
	v_cvt_f32_u32_e32 v181, v126
	v_mul_f32_e32 v122, v122, v182
	v_mul_f32_e32 v125, v121, v122
	v_fma_f32 v176, v120, v124, -v125
	v_mul_f32_e32 v126, v120, v122
	v_mul_f32_e32 v120, v218, v181
	v_fmac_f32_e32 v126, v121, v124
	v_fma_f32 v121, v181, v218, -v120
	v_floor_f32_e32 v120, v120
	v_fma_f32 v120, v218, v181, -v120
	v_add_f32_e32 v120, v121, v120
	v_sin_f32_e32 v121, v120
	v_cos_f32_e32 v120, v120
	v_mul_f32_e32 v123, v123, v183
	v_mul_f32_e32 v122, v127, v183
	v_mul_f32_e32 v124, v121, v123
	v_mul_f32_e32 v127, v120, v123
	v_fma_f32 v179, v120, v122, -v124
	v_fmac_f32_e32 v127, v121, v122
	v_or_b32_e32 v120, v144, v152
	v_mov_b32_e32 v121, v145
	v_xor_b32_e32 v124, 0x7f, v159
	v_lshlrev_b64 v[120:121], 9, v[120:121]
	v_sub_u32_e32 v125, 0x7e, v159
	v_sub_u32_e32 v133, 0x7d, v159
	v_sub_u32_e32 v156, 0x7c, v159
	v_lshlrev_b32_e32 v159, 1, v152
	s_and_b64 vcc, exec, s[0:1]
	v_lshl_add_u64 v[122:123], s[16:17], 0, v[120:121]
	v_lshlrev_b32_e32 v152, 1, v197
	v_cvt_f32_ubyte0_e32 v177, v124
	v_cvt_f32_ubyte0_e32 v175, v125
	v_cvt_f32_ubyte0_e32 v164, v133
	v_cvt_f32_ubyte0_e32 v162, v156
	v_and_or_b32 v156, v159, s50, v128
	s_cbranch_vccz .LBB0_214
	v_mul_f32_e32 v133, 0x3d800000, v157
	v_mul_f32_e32 v182, 0x3d800000, v163
	v_bfe_u32 v124, v133, 16, 1
	v_bfe_u32 v183, v182, 16, 1
	v_add3_u32 v180, v133, v124, s47
	v_lshl_add_u64 v[124:125], v[122:123], 0, v[152:153]
	v_mul_f32_e32 v184, 0x3d800000, v161
	v_add3_u32 v183, v182, v183, s47
	global_store_short_d16_hi v[124:125], v183, off offset:512
	v_bfe_u32 v183, v184, 16, 1
	v_add3_u32 v183, v184, v183, s47
	global_store_short_d16_hi v[124:125], v183, off offset:544
	v_mul_f32_e32 v183, v137, v175
	v_mul_f32_e32 v183, 0x3fb8aa3b, v183
	v_exp_f32_e32 v185, v183
	v_mul_f32_e32 v183, 0x3d800000, v176
	v_mul_f32_e32 v188, 0x3d800000, v179
	v_bfe_u32 v187, v183, 16, 1
	v_bfe_u32 v190, v188, 16, 1
	v_mul_f32_e32 v159, 0x3d800000, v155
	v_mul_f32_e32 v186, 0x3d800000, v126
	v_add3_u32 v187, v183, v187, s47
	v_mul_f32_e32 v189, 0x3d800000, v127
	v_add3_u32 v190, v188, v190, s47
	global_store_short_d16_hi v[124:125], v180, off
	v_bfe_u32 v180, v159, 16, 1
	global_store_short_d16_hi v[124:125], v187, off offset:1024
	v_bfe_u32 v187, v186, 16, 1
	global_store_short_d16_hi v[124:125], v190, off offset:1536
	v_bfe_u32 v190, v189, 16, 1
	v_add3_u32 v180, v159, v180, s47
	v_add3_u32 v187, v186, v187, s47
	v_add3_u32 v190, v189, v190, s47
	global_store_short_d16_hi v[124:125], v180, off offset:32
	v_mul_f32_e32 v180, v137, v177
	global_store_short_d16_hi v[124:125], v187, off offset:1056
	global_store_short_d16_hi v[124:125], v190, off offset:1568
	v_mul_f32_e32 v124, v137, v162
	v_mul_f32_e32 v180, 0x3fb8aa3b, v180
	v_mul_f32_e32 v187, v137, v164
	v_mul_f32_e32 v124, 0x3fb8aa3b, v124
	v_exp_f32_e32 v180, v180
	v_mul_f32_e32 v187, 0x3fb8aa3b, v187
	v_exp_f32_e32 v190, v124
	v_exp_f32_e32 v187, v187
	v_mul_f32_e32 v124, v180, v133
	v_mul_f32_e32 v125, v185, v182
	v_mul_f32_e32 v182, v190, v188
	v_mul_f32_e32 v133, v187, v183
	v_cvt_pk_bf16_f32 v124, v124, v125
	v_cvt_pk_bf16_f32 v125, v133, v182
	v_or_b32_e32 v182, v156, v197
	v_mov_b32_e32 v183, v129
	v_and_b32_e32 v182, -16, v182
	v_lshlrev_b64 v[182:183], 8, v[182:183]
	v_lshl_add_u64 v[182:183], s[20:21], 0, v[182:183]
	v_mov_b32_e32 v133, v153
	v_lshl_add_u64 v[182:183], v[182:183], 0, v[252:253]
	global_store_dwordx2 v[182:183], v[124:125], off
	v_or_b32_e32 v182, v156, v195
	v_mov_b32_e32 v183, v129
	v_and_b32_e32 v182, -16, v182
	v_lshlrev_b64 v[182:183], 8, v[182:183]
	v_lshl_add_u64 v[182:183], s[20:21], 0, v[182:183]
	v_mul_f32_e32 v124, v180, v159
	v_mul_f32_e32 v125, v185, v184
	v_lshl_add_u64 v[182:183], v[182:183], 0, v[252:253]
	v_mul_f32_e32 v159, v187, v186
	v_mul_f32_e32 v180, v190, v189
	v_cvt_pk_bf16_f32 v124, v124, v125
	v_cvt_pk_bf16_f32 v125, v159, v180
	global_store_dwordx2 v[182:183], v[124:125], off
	s_mov_b64 s[4:5], 0

.LBB0_216:
	v_lshl_add_u64 v[126:127], v[150:151], 2, s[8:9]
	v_subrev_u32_e32 v133, s8, v126
	v_and_b32_e32 v133, 0x3ff, v133
	ds_read_b32 v133, v133 offset:49152
	ds_read2_b32 v[188:189], v255 offset0:17 offset1:18
	ds_read_b32 v190, v255 offset:76
	v_bitop3_b32 v151, v136, s51, 16 bitop3:0xc8
	v_and_b32_e32 v182, 28, v150
	v_bitop3_b32 v163, v150, s38, 28 bitop3:0x6c
	v_bitop3_b32 v161, v150, s48, 28 bitop3:0x6c
	v_bitop3_b32 v159, v150, s49, 28 bitop3:0x6c
	v_bitop3_b32 v157, v150, s42, 28 bitop3:0x6c
	v_cvt_f32_u32_e32 v183, v151
	v_or_b32_e32 v150, 1, v151
	v_or_b32_e32 v176, 2, v151
	v_or_b32_e32 v179, 3, v151
	v_cvt_f32_u32_e32 v184, v150
	v_cvt_f32_u32_e32 v185, v176
	v_cvt_f32_u32_e32 v186, v179
	v_mul_f32_e32 v176, v218, v183
	v_fma_f32 v179, v183, v218, -v176
	v_floor_f32_e32 v176, v176
	v_mul_f32_e32 v180, v218, v184
	v_mul_f32_e32 v187, v218, v185
	v_mul_f32_e32 v191, v218, v186
	v_fma_f32 v176, v218, v183, -v176
	v_fma_f32 v192, v184, v218, -v180
	v_floor_f32_e32 v180, v180
	v_fma_f32 v193, v185, v218, -v187
	v_floor_f32_e32 v187, v187
	v_fma_f32 v194, v186, v218, -v191
	v_floor_f32_e32 v191, v191
	v_add_f32_e32 v176, v179, v176
	v_fma_f32 v179, v218, v184, -v180
	v_fma_f32 v180, v218, v185, -v187
	v_fma_f32 v187, v218, v186, -v191
	v_add_f32_e32 v179, v192, v179
	v_add_f32_e32 v180, v193, v180
	v_add_f32_e32 v187, v194, v187
	v_sin_f32_e32 v191, v176
	v_cos_f32_e32 v176, v176
	v_sin_f32_e32 v192, v179
	v_cos_f32_e32 v179, v179
	v_sin_f32_e32 v193, v180
	v_cos_f32_e32 v194, v180
	v_sin_f32_e32 v196, v187
	v_cos_f32_e32 v187, v187
	v_mov_b32_e32 v121, v145
	v_cndmask_b32_e64 v155, 0, 1, s[0:1]
	v_or_b32_e32 v120, v144, v151
	v_cmp_ne_u32_e64 s[4:5], 1, v155
	v_lshlrev_b32_e32 v155, 1, v151
	v_lshlrev_b64 v[150:151], 9, v[120:121]
	s_mov_b64 s[26:27], -1
	s_andn2_b64 vcc, exec, s[0:1]
	v_and_or_b32 v155, v155, s50, v128
	v_lshl_add_u64 v[120:121], s[16:17], 0, v[150:151]
	s_waitcnt lgkmcnt(0)
	v_mul_f32_e32 v112, v112, v133
	s_waitcnt lgkmcnt(0)
	v_mul_f32_e32 v117, v117, v188
	v_mul_f32_e32 v113, v113, v188
	v_mul_f32_e32 v188, v118, v189
	v_mul_f32_e32 v114, v114, v189
	v_mul_f32_e32 v189, v119, v190
	v_mul_f32_e32 v119, v115, v190
	v_mul_f32_e32 v116, v116, v133
	v_mul_f32_e32 v180, v191, v112
	v_mul_f32_e32 v133, v176, v112
	v_mul_f32_e32 v112, v192, v113
	v_mul_f32_e32 v118, v179, v113
	v_mul_f32_e32 v113, v193, v114
	v_mul_f32_e32 v115, v194, v114
	v_mul_f32_e32 v190, v196, v119
	v_mul_f32_e32 v114, v187, v119
	v_fma_f32 v180, v176, v116, -v180
	v_fmac_f32_e32 v133, v191, v116
	v_fma_f32 v179, v179, v117, -v112
	v_fmac_f32_e32 v118, v192, v117
	v_fma_f32 v176, v194, v188, -v113
	v_fmac_f32_e32 v115, v193, v188
	v_fma_f32 v119, v187, v189, -v190
	v_fmac_f32_e32 v114, v196, v189
	v_lshlrev_b32_e32 v112, 1, v182
	s_cbranch_vccnz .LBB0_218
	v_mul_f32_e32 v113, 0x3d800000, v180
	v_mul_f32_e32 v188, 0x3d800000, v179
	v_bfe_u32 v116, v113, 16, 1
	v_bfe_u32 v189, v188, 16, 1
	v_add3_u32 v187, v113, v116, s47
	v_lshl_add_u64 v[116:117], v[120:121], 0, v[152:153]
	v_mul_f32_e32 v190, 0x3d800000, v118
	v_add3_u32 v189, v188, v189, s47
	global_store_short_d16_hi v[116:117], v189, off offset:512
	v_bfe_u32 v189, v190, 16, 1
	v_add3_u32 v189, v190, v189, s47
	global_store_short_d16_hi v[116:117], v189, off offset:544
	v_cvt_f32_ubyte0_e32 v189, v161
	v_mul_f32_e32 v189, v137, v189
	v_mul_f32_e32 v189, 0x3fb8aa3b, v189
	v_exp_f32_e32 v191, v189
	v_mul_f32_e32 v189, 0x3d800000, v176
	v_mul_f32_e32 v194, 0x3d800000, v119
	v_bfe_u32 v193, v189, 16, 1
	v_bfe_u32 v198, v194, 16, 1
	v_mul_f32_e32 v182, 0x3d800000, v133
	v_mul_f32_e32 v192, 0x3d800000, v115
	v_add3_u32 v193, v189, v193, s47
	v_mul_f32_e32 v196, 0x3d800000, v114
	v_add3_u32 v198, v194, v198, s47
	global_store_short_d16_hi v[116:117], v187, off
	v_bfe_u32 v187, v182, 16, 1
	global_store_short_d16_hi v[116:117], v193, off offset:1024
	v_bfe_u32 v193, v192, 16, 1
	global_store_short_d16_hi v[116:117], v198, off offset:1536
	v_bfe_u32 v198, v196, 16, 1
	v_add3_u32 v187, v182, v187, s47
	v_add3_u32 v193, v192, v193, s47
	v_add3_u32 v198, v196, v198, s47
	global_store_short_d16_hi v[116:117], v187, off offset:32
	global_store_short_d16_hi v[116:117], v193, off offset:1056
	v_cvt_f32_ubyte0_e32 v193, v159
	global_store_short_d16_hi v[116:117], v198, off offset:1568
	v_cvt_f32_ubyte0_e32 v116, v157
	v_mul_f32_e32 v193, v137, v193
	v_mul_f32_e32 v116, v137, v116
	v_cvt_f32_ubyte0_e32 v187, v163
	v_mul_f32_e32 v193, 0x3fb8aa3b, v193
	v_mul_f32_e32 v116, 0x3fb8aa3b, v116
	v_mul_f32_e32 v187, v137, v187
	v_exp_f32_e32 v193, v193
	v_exp_f32_e32 v198, v116
	v_mul_f32_e32 v187, 0x3fb8aa3b, v187
	v_exp_f32_e32 v187, v187
	v_mul_f32_e32 v116, v191, v188
	v_mul_f32_e32 v117, v193, v189
	v_mul_f32_e32 v188, v198, v194
	v_cvt_pk_bf16_f32 v117, v117, v188
	v_or_b32_e32 v188, v155, v197
	v_mov_b32_e32 v189, v129
	v_mul_f32_e32 v113, v187, v113
	v_and_b32_e32 v188, -16, v188
	v_lshlrev_b64 v[188:189], 8, v[188:189]
	v_cvt_pk_bf16_f32 v116, v113, v116
	v_lshl_add_u64 v[188:189], s[20:21], 0, v[188:189]
	v_mov_b32_e32 v113, v153
	v_lshl_add_u64 v[188:189], v[188:189], 0, v[252:253]
	global_store_dwordx2 v[188:189], v[116:117], off offset:512
	v_or_b32_e32 v188, v155, v195
	v_mov_b32_e32 v189, v129
	v_and_b32_e32 v188, -16, v188
	v_lshlrev_b64 v[188:189], 8, v[188:189]
	v_lshl_add_u64 v[188:189], s[20:21], 0, v[188:189]
	v_mul_f32_e32 v116, v187, v182
	v_mul_f32_e32 v117, v191, v190
	v_lshl_add_u64 v[188:189], v[188:189], 0, v[252:253]
	s_mov_b64 s[26:27], 0
	v_mul_f32_e32 v182, v193, v192
	v_mul_f32_e32 v187, v198, v196
	v_cvt_pk_bf16_f32 v116, v116, v117
	v_cvt_pk_bf16_f32 v117, v182, v187
	global_store_dwordx2 v[188:189], v[116:117], off offset:512

.LBB0_220:
	v_lshl_add_u64 v[118:119], v[148:149], 2, s[8:9]
	v_subrev_u32_e32 v113, s8, v118
	v_and_b32_e32 v113, 0x3ff, v113
	ds_read_b32 v113, v113 offset:49152
	ds_read2_b32 v[198:199], v255 offset0:33 offset1:34
	ds_read_b32 v200, v255 offset:140
	v_bitop3_b32 v133, v136, s56, 32 bitop3:0xc8
	v_and_b32_e32 v188, 44, v148
	v_bitop3_b32 v180, v148, s38, 44 bitop3:0x6c
	v_bitop3_b32 v179, v148, s48, 44 bitop3:0x6c
	v_bitop3_b32 v176, v148, s49, 44 bitop3:0x6c
	v_bitop3_b32 v151, v148, s42, 44 bitop3:0x6c
	v_cvt_f32_u32_e32 v190, v133
	v_or_b32_e32 v148, 1, v133
	v_or_b32_e32 v149, 2, v133
	v_or_b32_e32 v150, 3, v133
	v_cvt_f32_u32_e32 v191, v148
	v_cvt_f32_u32_e32 v192, v149
	v_cvt_f32_u32_e32 v193, v150
	v_or_b32_e32 v114, v144, v133
	v_lshlrev_b32_e32 v133, 1, v133
	v_and_or_b32 v150, v133, s50, v128
	v_mul_f32_e32 v133, v218, v190
	v_fma_f32 v182, v190, v218, -v133
	v_floor_f32_e32 v133, v133
	v_mul_f32_e32 v187, v218, v191
	v_mul_f32_e32 v189, v218, v192
	v_mul_f32_e32 v194, v218, v193
	v_fma_f32 v133, v218, v190, -v133
	v_fma_f32 v196, v191, v218, -v187
	v_floor_f32_e32 v187, v187
	v_fma_f32 v201, v192, v218, -v189
	v_floor_f32_e32 v189, v189
	v_fma_f32 v202, v193, v218, -v194
	v_floor_f32_e32 v194, v194
	v_add_f32_e32 v133, v182, v133
	v_fma_f32 v182, v218, v191, -v187
	v_fma_f32 v187, v218, v192, -v189
	v_fma_f32 v189, v218, v193, -v194
	v_add_f32_e32 v182, v196, v182
	v_add_f32_e32 v187, v201, v187
	v_add_f32_e32 v189, v202, v189
	v_sin_f32_e32 v194, v133
	v_cos_f32_e32 v133, v133
	v_sin_f32_e32 v196, v182
	v_cos_f32_e32 v182, v182
	v_sin_f32_e32 v201, v187
	v_cos_f32_e32 v202, v187
	v_sin_f32_e32 v203, v189
	v_cos_f32_e32 v189, v189
	v_mov_b32_e32 v115, v145
	v_lshlrev_b64 v[148:149], 9, v[114:115]
	s_mov_b64 s[0:1], -1
	s_and_b64 vcc, exec, s[4:5]
	v_lshl_add_u64 v[114:115], s[16:17], 0, v[148:149]
	s_waitcnt lgkmcnt(0)
	v_mul_f32_e32 v104, v104, v113
	s_waitcnt lgkmcnt(0)
	v_mul_f32_e32 v109, v109, v198
	v_mul_f32_e32 v105, v105, v198
	v_mul_f32_e32 v198, v110, v199
	v_mul_f32_e32 v106, v106, v199
	v_mul_f32_e32 v199, v111, v200
	v_mul_f32_e32 v111, v107, v200
	v_mul_f32_e32 v108, v108, v113
	v_mul_f32_e32 v187, v194, v104
	v_mul_f32_e32 v113, v133, v104
	v_mul_f32_e32 v104, v196, v105
	v_mul_f32_e32 v110, v182, v105
	v_mul_f32_e32 v105, v201, v106
	v_mul_f32_e32 v107, v202, v106
	v_mul_f32_e32 v200, v203, v111
	v_mul_f32_e32 v106, v189, v111
	v_fma_f32 v187, v133, v108, -v187
	v_fmac_f32_e32 v113, v194, v108
	v_fma_f32 v182, v182, v109, -v104
	v_fmac_f32_e32 v110, v196, v109
	v_fma_f32 v133, v202, v198, -v105
	v_fmac_f32_e32 v107, v201, v198
	v_fma_f32 v111, v189, v199, -v200
	v_fmac_f32_e32 v106, v203, v199
	v_lshlrev_b32_e32 v104, 1, v188
	s_cbranch_vccnz .LBB0_222
	v_mul_f32_e32 v105, 0x3d800000, v187
	v_bfe_u32 v108, v105, 16, 1
	v_mul_f32_e32 v194, 0x3d800000, v113
	v_add3_u32 v188, v105, v108, s47
	v_lshl_add_u64 v[108:109], v[114:115], 0, v[152:153]
	global_store_short_d16_hi v[108:109], v188, off
	v_bfe_u32 v188, v194, 16, 1
	v_add3_u32 v188, v194, v188, s47
	global_store_short_d16_hi v[108:109], v188, off offset:32
	v_cvt_f32_ubyte0_e32 v188, v180
	v_mul_f32_e32 v188, v137, v188
	v_mul_f32_e32 v188, 0x3fb8aa3b, v188
	v_exp_f32_e32 v196, v188
	v_mul_f32_e32 v188, 0x3d800000, v182
	v_bfe_u32 v189, v188, 16, 1
	v_mul_f32_e32 v198, 0x3d800000, v110
	v_add3_u32 v189, v188, v189, s47
	global_store_short_d16_hi v[108:109], v189, off offset:512
	v_bfe_u32 v189, v198, 16, 1
	v_add3_u32 v189, v198, v189, s47
	global_store_short_d16_hi v[108:109], v189, off offset:544
	v_cvt_f32_ubyte0_e32 v189, v179
	v_mul_f32_e32 v189, v137, v189
	v_mul_f32_e32 v189, 0x3fb8aa3b, v189
	v_exp_f32_e32 v199, v189
	v_mul_f32_e32 v189, 0x3d800000, v133
	v_mul_f32_e32 v202, 0x3d800000, v111
	v_bfe_u32 v201, v189, 16, 1
	v_bfe_u32 v204, v202, 16, 1
	v_mul_f32_e32 v200, 0x3d800000, v107
	v_add3_u32 v201, v189, v201, s47
	v_mul_f32_e32 v203, 0x3d800000, v106
	v_add3_u32 v204, v202, v204, s47
	global_store_short_d16_hi v[108:109], v201, off offset:1024
	v_bfe_u32 v201, v200, 16, 1
	global_store_short_d16_hi v[108:109], v204, off offset:1536
	v_bfe_u32 v204, v203, 16, 1
	v_add3_u32 v201, v200, v201, s47
	v_add3_u32 v204, v203, v204, s47
	global_store_short_d16_hi v[108:109], v201, off offset:1056
	v_cvt_f32_ubyte0_e32 v201, v176
	global_store_short_d16_hi v[108:109], v204, off offset:1568
	v_cvt_f32_ubyte0_e32 v108, v151
	v_mul_f32_e32 v201, v137, v201
	v_mul_f32_e32 v108, v137, v108
	v_mul_f32_e32 v201, 0x3fb8aa3b, v201
	v_mul_f32_e32 v108, 0x3fb8aa3b, v108
	v_exp_f32_e32 v201, v201
	v_exp_f32_e32 v204, v108
	v_mul_f32_e32 v108, v199, v188
	v_mul_f32_e32 v105, v196, v105
	v_mul_f32_e32 v109, v201, v189
	v_mul_f32_e32 v188, v204, v202
	v_cvt_pk_bf16_f32 v109, v109, v188
	v_or_b32_e32 v188, v150, v197
	v_mov_b32_e32 v189, v129
	v_and_b32_e32 v188, -16, v188
	v_lshlrev_b64 v[188:189], 8, v[188:189]
	v_cvt_pk_bf16_f32 v108, v105, v108
	v_lshl_add_u64 v[188:189], s[20:21], 0, v[188:189]
	v_mov_b32_e32 v105, v153
	v_lshl_add_u64 v[188:189], v[188:189], 0, v[252:253]
	global_store_dwordx2 v[188:189], v[108:109], off offset:1024
	v_mul_f32_e32 v108, v196, v194
	v_mul_f32_e32 v109, v199, v198
	v_mul_f32_e32 v188, v201, v200
	v_mul_f32_e32 v189, v204, v203
	v_cvt_pk_bf16_f32 v108, v108, v109
	v_cvt_pk_bf16_f32 v109, v188, v189
	v_or_b32_e32 v188, v150, v195
	v_mov_b32_e32 v189, v129
	v_and_b32_e32 v188, -16, v188
	v_lshlrev_b64 v[188:189], 8, v[188:189]
	v_lshl_add_u64 v[188:189], s[20:21], 0, v[188:189]
	v_lshl_add_u64 v[188:189], v[188:189], 0, v[252:253]
	s_mov_b64 s[0:1], 0
	global_store_dwordx2 v[188:189], v[108:109], off offset:1024

.LBB0_224:
	v_lshl_add_u64 v[110:111], v[146:147], 2, s[8:9]
	v_subrev_u32_e32 v105, s8, v110
	v_and_b32_e32 v105, 0x3ff, v105
	ds_read_b32 v105, v105 offset:49152
	ds_read2_b32 v[204:205], v255 offset0:49 offset1:50
	ds_read_b32 v206, v255 offset:204
	v_bitop3_b32 v113, v136, s57, 48 bitop3:0xc8
	v_and_b32_e32 v194, 60, v146
	v_bitop3_b32 v188, v146, s38, 60 bitop3:0x6c
	v_bitop3_b32 v187, v146, s48, 60 bitop3:0x6c
	v_bitop3_b32 v182, v146, s49, 60 bitop3:0x6c
	v_bitop3_b32 v149, v146, s42, 60 bitop3:0x6c
	v_cvt_f32_u32_e32 v199, v113
	v_or_b32_e32 v133, 1, v113
	v_or_b32_e32 v146, 2, v113
	v_or_b32_e32 v147, 3, v113
	v_cvt_f32_u32_e32 v200, v133
	v_cvt_f32_u32_e32 v201, v146
	v_cvt_f32_u32_e32 v202, v147
	v_or_b32_e32 v106, v144, v113
	v_lshlrev_b32_e32 v113, 1, v113
	v_and_or_b32 v148, v113, s50, v128
	v_mul_f32_e32 v113, v218, v199
	v_fma_f32 v133, v199, v218, -v113
	v_floor_f32_e32 v113, v113
	v_mul_f32_e32 v189, v218, v200
	v_mul_f32_e32 v196, v218, v201
	v_mul_f32_e32 v198, v218, v202
	v_fma_f32 v113, v218, v199, -v113
	v_fma_f32 v203, v200, v218, -v189
	v_floor_f32_e32 v189, v189
	v_fma_f32 v207, v201, v218, -v196
	v_floor_f32_e32 v196, v196
	v_fma_f32 v208, v202, v218, -v198
	v_floor_f32_e32 v198, v198
	v_add_f32_e32 v113, v133, v113
	v_fma_f32 v133, v218, v200, -v189
	v_fma_f32 v189, v218, v201, -v196
	v_fma_f32 v196, v218, v202, -v198
	v_add_f32_e32 v133, v203, v133
	v_add_f32_e32 v189, v207, v189
	v_add_f32_e32 v196, v208, v196
	v_sin_f32_e32 v198, v113
	v_cos_f32_e32 v113, v113
	v_sin_f32_e32 v203, v133
	v_cos_f32_e32 v133, v133
	v_sin_f32_e32 v207, v189
	v_cos_f32_e32 v208, v189
	v_sin_f32_e32 v209, v196
	v_cos_f32_e32 v196, v196
	v_mov_b32_e32 v107, v145
	v_lshlrev_b64 v[146:147], 9, v[106:107]
	s_mov_b64 s[0:1], -1
	s_and_b64 vcc, exec, s[4:5]
	v_lshl_add_u64 v[106:107], s[16:17], 0, v[146:147]
	s_waitcnt lgkmcnt(0)
	v_mul_f32_e32 v96, v96, v105
	s_waitcnt lgkmcnt(0)
	v_mul_f32_e32 v101, v101, v204
	v_mul_f32_e32 v97, v97, v204
	v_mul_f32_e32 v204, v102, v205
	v_mul_f32_e32 v98, v98, v205
	v_mul_f32_e32 v205, v103, v206
	v_mul_f32_e32 v103, v99, v206
	v_mul_f32_e32 v100, v100, v105
	v_mul_f32_e32 v189, v198, v96
	v_mul_f32_e32 v105, v113, v96
	v_mul_f32_e32 v96, v203, v97
	v_mul_f32_e32 v102, v133, v97
	v_mul_f32_e32 v97, v207, v98
	v_mul_f32_e32 v99, v208, v98
	v_mul_f32_e32 v206, v209, v103
	v_mul_f32_e32 v98, v196, v103
	v_fma_f32 v189, v113, v100, -v189
	v_fmac_f32_e32 v105, v198, v100
	v_fma_f32 v133, v133, v101, -v96
	v_fmac_f32_e32 v102, v203, v101
	v_fma_f32 v113, v208, v204, -v97
	v_fmac_f32_e32 v99, v207, v204
	v_fma_f32 v103, v196, v205, -v206
	v_fmac_f32_e32 v98, v209, v205
	v_lshlrev_b32_e32 v96, 1, v194
	s_cbranch_vccnz .LBB0_226
	v_mul_f32_e32 v97, 0x3d800000, v189
	v_mul_f32_e32 v198, 0x3d800000, v133
	v_bfe_u32 v100, v97, 16, 1
	v_bfe_u32 v204, v198, 16, 1
	v_add3_u32 v196, v97, v100, s47
	v_lshl_add_u64 v[100:101], v[106:107], 0, v[152:153]
	v_mul_f32_e32 v203, 0x3d800000, v102
	v_add3_u32 v204, v198, v204, s47
	global_store_short_d16_hi v[100:101], v204, off offset:512
	v_bfe_u32 v204, v203, 16, 1
	v_add3_u32 v204, v203, v204, s47
	global_store_short_d16_hi v[100:101], v204, off offset:544
	v_cvt_f32_ubyte0_e32 v204, v187
	v_mul_f32_e32 v204, v137, v204
	v_mul_f32_e32 v204, 0x3fb8aa3b, v204
	v_exp_f32_e32 v206, v204
	v_mul_f32_e32 v204, 0x3d800000, v113
	v_bfe_u32 v205, v204, 16, 1
	v_mul_f32_e32 v207, 0x3d800000, v99
	v_add3_u32 v205, v204, v205, s47
	global_store_short_d16_hi v[100:101], v205, off offset:1024
	v_bfe_u32 v205, v207, 16, 1
	v_add3_u32 v205, v207, v205, s47
	global_store_short_d16_hi v[100:101], v205, off offset:1056
	v_cvt_f32_ubyte0_e32 v205, v182
	v_mul_f32_e32 v205, v137, v205
	v_mul_f32_e32 v205, 0x3fb8aa3b, v205
	v_exp_f32_e32 v208, v205
	v_mul_f32_e32 v205, 0x3d800000, v103
	v_bfe_u32 v210, v205, 16, 1
	v_mul_f32_e32 v194, 0x3d800000, v105
	v_mul_f32_e32 v209, 0x3d800000, v98
	v_add3_u32 v210, v205, v210, s47
	global_store_short_d16_hi v[100:101], v196, off
	v_bfe_u32 v196, v194, 16, 1
	global_store_short_d16_hi v[100:101], v210, off offset:1536
	v_bfe_u32 v210, v209, 16, 1
	v_add3_u32 v196, v194, v196, s47
	v_add3_u32 v210, v209, v210, s47
	global_store_short_d16_hi v[100:101], v196, off offset:32
	global_store_short_d16_hi v[100:101], v210, off offset:1568
	v_cvt_f32_ubyte0_e32 v100, v149
	v_cvt_f32_ubyte0_e32 v196, v188
	v_mul_f32_e32 v100, v137, v100
	v_mul_f32_e32 v196, v137, v196
	v_mul_f32_e32 v100, 0x3fb8aa3b, v100
	v_mul_f32_e32 v196, 0x3fb8aa3b, v196
	v_exp_f32_e32 v210, v100
	v_exp_f32_e32 v196, v196
	v_mul_f32_e32 v100, v206, v198
	v_mul_f32_e32 v101, v208, v204
	v_mul_f32_e32 v198, v210, v205
	v_or_b32_e32 v204, v148, v197
	v_mov_b32_e32 v205, v129
	v_mul_f32_e32 v97, v196, v97
	v_and_b32_e32 v204, -16, v204
	v_lshlrev_b64 v[204:205], 8, v[204:205]
	v_cvt_pk_bf16_f32 v100, v97, v100
	v_lshl_add_u64 v[204:205], s[20:21], 0, v[204:205]
	v_mov_b32_e32 v97, v153
	v_lshl_add_u64 v[204:205], v[204:205], 0, v[252:253]
	v_cvt_pk_bf16_f32 v101, v101, v198
	global_store_dwordx2 v[204:205], v[100:101], off offset:1536
	v_or_b32_e32 v204, v148, v195
	v_mov_b32_e32 v205, v129
	v_and_b32_e32 v204, -16, v204
	v_lshlrev_b64 v[204:205], 8, v[204:205]
	v_lshl_add_u64 v[204:205], s[20:21], 0, v[204:205]
	v_mul_f32_e32 v100, v196, v194
	v_mul_f32_e32 v101, v206, v203
	v_lshl_add_u64 v[204:205], v[204:205], 0, v[252:253]
	s_mov_b64 s[0:1], 0
	v_mul_f32_e32 v194, v208, v207
	v_mul_f32_e32 v196, v210, v209
	v_cvt_pk_bf16_f32 v100, v100, v101
	v_cvt_pk_bf16_f32 v101, v194, v196
	global_store_dwordx2 v[204:205], v[100:101], off offset:1536

.LBB0_228:
	v_lshl_add_u64 v[102:103], v[142:143], 2, s[8:9]
	v_subrev_u32_e32 v97, s8, v102
	v_and_b32_e32 v97, 0x3ff, v97
	ds_read_b32 v97, v97 offset:49152
	ds_read2_b32 v[210:211], v255 offset0:65 offset1:66
	ds_read_b32 v212, v255 offset:268
	v_bitop3_b32 v105, v136, s58, 64 bitop3:0xc8
	v_and_b32_e32 v198, 0x4c, v142
	v_bitop3_b32 v196, v142, s38, v171 bitop3:0x6c
	v_bitop3_b32 v194, v142, s48, v171 bitop3:0x6c
	v_bitop3_b32 v189, v142, s49, v171 bitop3:0x6c
	v_bitop3_b32 v147, v142, s42, v171 bitop3:0x6c
	v_cvt_f32_u32_e32 v206, v105
	v_or_b32_e32 v113, 1, v105
	v_or_b32_e32 v133, 2, v105
	v_or_b32_e32 v142, 3, v105
	v_cvt_f32_u32_e32 v207, v113
	v_cvt_f32_u32_e32 v208, v133
	v_cvt_f32_u32_e32 v209, v142
	v_or_b32_e32 v98, v144, v105
	v_lshlrev_b32_e32 v105, 1, v105
	v_and_or_b32 v146, v105, s50, v128
	v_mul_f32_e32 v105, v218, v206
	v_fma_f32 v113, v206, v218, -v105
	v_floor_f32_e32 v105, v105
	v_mul_f32_e32 v133, v218, v207
	v_mul_f32_e32 v203, v218, v208
	v_mul_f32_e32 v204, v218, v209
	v_fma_f32 v105, v218, v206, -v105
	v_fma_f32 v205, v207, v218, -v133
	v_floor_f32_e32 v133, v133
	v_fma_f32 v213, v208, v218, -v203
	v_floor_f32_e32 v203, v203
	v_fma_f32 v214, v209, v218, -v204
	v_floor_f32_e32 v204, v204
	v_add_f32_e32 v105, v113, v105
	v_fma_f32 v113, v218, v207, -v133
	v_fma_f32 v133, v218, v208, -v203
	v_fma_f32 v203, v218, v209, -v204
	v_add_f32_e32 v113, v205, v113
	v_add_f32_e32 v133, v213, v133
	v_add_f32_e32 v203, v214, v203
	v_sin_f32_e32 v204, v105
	v_cos_f32_e32 v105, v105
	v_sin_f32_e32 v205, v113
	v_cos_f32_e32 v113, v113
	v_sin_f32_e32 v213, v133
	v_cos_f32_e32 v214, v133
	v_sin_f32_e32 v215, v203
	v_cos_f32_e32 v203, v203
	v_mov_b32_e32 v99, v145
	v_lshlrev_b64 v[142:143], 9, v[98:99]
	s_mov_b64 s[0:1], -1
	s_and_b64 vcc, exec, s[4:5]
	v_lshl_add_u64 v[98:99], s[16:17], 0, v[142:143]
	s_waitcnt lgkmcnt(0)
	v_mul_f32_e32 v88, v88, v97
	s_waitcnt lgkmcnt(0)
	v_mul_f32_e32 v93, v93, v210
	v_mul_f32_e32 v89, v89, v210
	v_mul_f32_e32 v210, v94, v211
	v_mul_f32_e32 v90, v90, v211
	v_mul_f32_e32 v211, v95, v212
	v_mul_f32_e32 v95, v91, v212
	v_mul_f32_e32 v92, v92, v97
	v_mul_f32_e32 v133, v204, v88
	v_mul_f32_e32 v97, v105, v88
	v_mul_f32_e32 v88, v205, v89
	v_mul_f32_e32 v94, v113, v89
	v_mul_f32_e32 v89, v213, v90
	v_mul_f32_e32 v91, v214, v90
	v_mul_f32_e32 v212, v215, v95
	v_mul_f32_e32 v90, v203, v95
	v_fma_f32 v133, v105, v92, -v133
	v_fmac_f32_e32 v97, v204, v92
	v_fma_f32 v113, v113, v93, -v88
	v_fmac_f32_e32 v94, v205, v93
	v_fma_f32 v105, v214, v210, -v89
	v_fmac_f32_e32 v91, v213, v210
	v_fma_f32 v95, v203, v211, -v212
	v_fmac_f32_e32 v90, v215, v211
	v_lshlrev_b32_e32 v88, 1, v198
	s_cbranch_vccnz .LBB0_230
	v_mul_f32_e32 v89, 0x3d800000, v133
	v_mul_f32_e32 v204, 0x3d800000, v113
	v_bfe_u32 v92, v89, 16, 1
	v_bfe_u32 v205, v204, 16, 1
	v_add3_u32 v203, v89, v92, s47
	v_lshl_add_u64 v[92:93], v[98:99], 0, v[152:153]
	v_mul_f32_e32 v210, 0x3d800000, v94
	v_add3_u32 v205, v204, v205, s47
	global_store_short_d16_hi v[92:93], v205, off offset:512
	v_bfe_u32 v205, v210, 16, 1
	v_add3_u32 v205, v210, v205, s47
	global_store_short_d16_hi v[92:93], v205, off offset:544
	v_cvt_f32_ubyte0_e32 v205, v194
	v_mul_f32_e32 v205, v137, v205
	v_mul_f32_e32 v205, 0x3fb8aa3b, v205
	v_exp_f32_e32 v211, v205
	v_mul_f32_e32 v205, 0x3d800000, v105
	v_mul_f32_e32 v214, 0x3d800000, v95
	v_bfe_u32 v213, v205, 16, 1
	v_bfe_u32 v216, v214, 16, 1
	v_mul_f32_e32 v198, 0x3d800000, v97
	v_mul_f32_e32 v212, 0x3d800000, v91
	v_add3_u32 v213, v205, v213, s47
	v_mul_f32_e32 v215, 0x3d800000, v90
	v_add3_u32 v216, v214, v216, s47
	global_store_short_d16_hi v[92:93], v203, off
	v_bfe_u32 v203, v198, 16, 1
	global_store_short_d16_hi v[92:93], v213, off offset:1024
	v_bfe_u32 v213, v212, 16, 1
	global_store_short_d16_hi v[92:93], v216, off offset:1536
	v_bfe_u32 v216, v215, 16, 1
	v_add3_u32 v203, v198, v203, s47
	v_add3_u32 v213, v212, v213, s47
	v_add3_u32 v216, v215, v216, s47
	global_store_short_d16_hi v[92:93], v203, off offset:32
	global_store_short_d16_hi v[92:93], v213, off offset:1056
	v_cvt_f32_ubyte0_e32 v213, v189
	global_store_short_d16_hi v[92:93], v216, off offset:1568
	v_cvt_f32_ubyte0_e32 v92, v147
	v_mul_f32_e32 v213, v137, v213
	v_mul_f32_e32 v92, v137, v92
	v_cvt_f32_ubyte0_e32 v203, v196
	v_mul_f32_e32 v213, 0x3fb8aa3b, v213
	v_mul_f32_e32 v92, 0x3fb8aa3b, v92
	v_mul_f32_e32 v203, v137, v203
	v_exp_f32_e32 v213, v213
	v_exp_f32_e32 v216, v92
	v_mul_f32_e32 v203, 0x3fb8aa3b, v203
	v_exp_f32_e32 v203, v203
	v_mul_f32_e32 v92, v211, v204
	v_mul_f32_e32 v93, v213, v205
	v_mul_f32_e32 v204, v216, v214
	v_cvt_pk_bf16_f32 v93, v93, v204
	v_or_b32_e32 v204, v146, v197
	v_mov_b32_e32 v205, v129
	v_mul_f32_e32 v89, v203, v89
	v_and_b32_e32 v204, -16, v204
	v_lshlrev_b64 v[204:205], 8, v[204:205]
	v_cvt_pk_bf16_f32 v92, v89, v92
	v_lshl_add_u64 v[204:205], s[20:21], 0, v[204:205]
	v_mov_b32_e32 v89, v153
	v_lshl_add_u64 v[204:205], v[204:205], 0, v[252:253]
	global_store_dwordx2 v[204:205], v[92:93], off offset:2048
	v_or_b32_e32 v204, v146, v195
	v_mov_b32_e32 v205, v129
	v_and_b32_e32 v204, -16, v204
	v_lshlrev_b64 v[204:205], 8, v[204:205]
	v_lshl_add_u64 v[204:205], s[20:21], 0, v[204:205]
	v_mul_f32_e32 v92, v203, v198
	v_mul_f32_e32 v93, v211, v210
	v_lshl_add_u64 v[204:205], v[204:205], 0, v[252:253]
	s_mov_b64 s[0:1], 0
	v_mul_f32_e32 v198, v213, v212
	v_mul_f32_e32 v203, v216, v215
	v_cvt_pk_bf16_f32 v92, v92, v93
	v_cvt_pk_bf16_f32 v93, v198, v203
	global_store_dwordx2 v[204:205], v[92:93], off offset:2048

.LBB0_232:
	v_lshl_add_u64 v[94:95], v[140:141], 2, s[8:9]
	v_subrev_u32_e32 v89, s8, v94
	v_and_b32_e32 v89, 0x3ff, v89
	ds_read_b32 v89, v89 offset:49152
	ds_read2_b32 v[222:223], v255 offset0:81 offset1:82
	ds_read_b32 v224, v255 offset:332
	v_bitop3_b32 v97, v136, s59, v166 bitop3:0xc8
	v_and_b32_e32 v133, 0x5c, v140
	v_bitop3_b32 v204, v140, s38, v172 bitop3:0x6c
	v_bitop3_b32 v203, v140, s48, v172 bitop3:0x6c
	v_bitop3_b32 v198, v140, s49, v172 bitop3:0x6c
	v_bitop3_b32 v143, v140, s42, v172 bitop3:0x6c
	v_cvt_f32_u32_e32 v212, v97
	v_or_b32_e32 v105, 1, v97
	v_or_b32_e32 v113, 2, v97
	v_or_b32_e32 v140, 3, v97
	v_cvt_f32_u32_e32 v213, v105
	v_cvt_f32_u32_e32 v214, v113
	v_cvt_f32_u32_e32 v215, v140
	v_or_b32_e32 v90, v144, v97
	v_lshlrev_b32_e32 v97, 1, v97
	v_and_or_b32 v142, v97, s50, v128
	v_mul_f32_e32 v97, v218, v212
	v_fma_f32 v105, v212, v218, -v97
	v_floor_f32_e32 v97, v97
	v_mul_f32_e32 v113, v218, v213
	v_mul_f32_e32 v205, v218, v214
	v_mul_f32_e32 v210, v218, v215
	v_fma_f32 v97, v218, v212, -v97
	v_fma_f32 v211, v213, v218, -v113
	v_floor_f32_e32 v113, v113
	v_fma_f32 v216, v214, v218, -v205
	v_floor_f32_e32 v205, v205
	v_fma_f32 v217, v215, v218, -v210
	v_floor_f32_e32 v210, v210
	v_add_f32_e32 v97, v105, v97
	v_fma_f32 v105, v218, v213, -v113
	v_fma_f32 v113, v218, v214, -v205
	v_fma_f32 v205, v218, v215, -v210
	v_add_f32_e32 v105, v211, v105
	v_add_f32_e32 v113, v216, v113
	v_add_f32_e32 v205, v217, v205
	v_sin_f32_e32 v210, v97
	v_cos_f32_e32 v97, v97
	v_sin_f32_e32 v211, v105
	v_cos_f32_e32 v105, v105
	v_sin_f32_e32 v216, v113
	v_cos_f32_e32 v217, v113
	v_sin_f32_e32 v219, v205
	v_cos_f32_e32 v205, v205
	v_mov_b32_e32 v91, v145
	v_lshlrev_b64 v[140:141], 9, v[90:91]
	s_mov_b64 s[0:1], -1
	s_and_b64 vcc, exec, s[4:5]
	v_lshl_add_u64 v[90:91], s[16:17], 0, v[140:141]
	s_waitcnt lgkmcnt(0)
	v_mul_f32_e32 v80, v80, v89
	s_waitcnt lgkmcnt(0)
	v_mul_f32_e32 v85, v85, v222
	v_mul_f32_e32 v81, v81, v222
	v_mul_f32_e32 v222, v86, v223
	v_mul_f32_e32 v82, v82, v223
	v_mul_f32_e32 v223, v87, v224
	v_mul_f32_e32 v87, v83, v224
	v_mul_f32_e32 v84, v84, v89
	v_mul_f32_e32 v113, v210, v80
	v_mul_f32_e32 v89, v97, v80
	v_mul_f32_e32 v80, v211, v81
	v_mul_f32_e32 v86, v105, v81
	v_mul_f32_e32 v81, v216, v82
	v_mul_f32_e32 v83, v217, v82
	v_mul_f32_e32 v224, v219, v87
	v_mul_f32_e32 v82, v205, v87
	v_fma_f32 v113, v97, v84, -v113
	v_fmac_f32_e32 v89, v210, v84
	v_fma_f32 v105, v105, v85, -v80
	v_fmac_f32_e32 v86, v211, v85
	v_fma_f32 v97, v217, v222, -v81
	v_fmac_f32_e32 v83, v216, v222
	v_fma_f32 v87, v205, v223, -v224
	v_fmac_f32_e32 v82, v219, v223
	v_lshlrev_b32_e32 v80, 1, v133
	s_cbranch_vccnz .LBB0_234
	v_mul_f32_e32 v81, 0x3d800000, v113
	v_mul_f32_e32 v210, 0x3d800000, v105
	v_bfe_u32 v84, v81, 16, 1
	v_bfe_u32 v211, v210, 16, 1
	v_add3_u32 v205, v81, v84, s47
	v_lshl_add_u64 v[84:85], v[90:91], 0, v[152:153]
	v_mul_f32_e32 v216, 0x3d800000, v86
	v_add3_u32 v211, v210, v211, s47
	global_store_short_d16_hi v[84:85], v211, off offset:512
	v_bfe_u32 v211, v216, 16, 1
	v_add3_u32 v211, v216, v211, s47
	global_store_short_d16_hi v[84:85], v211, off offset:544
	v_cvt_f32_ubyte0_e32 v211, v203
	v_mul_f32_e32 v211, v137, v211
	v_mul_f32_e32 v211, 0x3fb8aa3b, v211
	v_exp_f32_e32 v217, v211
	v_mul_f32_e32 v211, 0x3d800000, v97
	v_mul_f32_e32 v223, 0x3d800000, v87
	v_bfe_u32 v222, v211, 16, 1
	v_bfe_u32 v225, v223, 16, 1
	v_mul_f32_e32 v133, 0x3d800000, v89
	v_mul_f32_e32 v219, 0x3d800000, v83
	v_add3_u32 v222, v211, v222, s47
	v_mul_f32_e32 v224, 0x3d800000, v82
	v_add3_u32 v225, v223, v225, s47
	global_store_short_d16_hi v[84:85], v205, off
	v_bfe_u32 v205, v133, 16, 1
	global_store_short_d16_hi v[84:85], v222, off offset:1024
	v_bfe_u32 v222, v219, 16, 1
	global_store_short_d16_hi v[84:85], v225, off offset:1536
	v_bfe_u32 v225, v224, 16, 1
	v_add3_u32 v205, v133, v205, s47
	v_add3_u32 v222, v219, v222, s47
	v_add3_u32 v225, v224, v225, s47
	global_store_short_d16_hi v[84:85], v205, off offset:32
	global_store_short_d16_hi v[84:85], v222, off offset:1056
	v_cvt_f32_ubyte0_e32 v222, v198
	global_store_short_d16_hi v[84:85], v225, off offset:1568
	v_cvt_f32_ubyte0_e32 v84, v143
	v_mul_f32_e32 v222, v137, v222
	v_mul_f32_e32 v84, v137, v84
	v_cvt_f32_ubyte0_e32 v205, v204
	v_mul_f32_e32 v222, 0x3fb8aa3b, v222
	v_mul_f32_e32 v84, 0x3fb8aa3b, v84
	v_mul_f32_e32 v205, v137, v205
	v_exp_f32_e32 v222, v222
	v_exp_f32_e32 v225, v84
	v_mul_f32_e32 v205, 0x3fb8aa3b, v205
	v_exp_f32_e32 v205, v205
	v_mul_f32_e32 v84, v217, v210
	v_mul_f32_e32 v85, v222, v211
	v_mul_f32_e32 v210, v225, v223
	v_cvt_pk_bf16_f32 v85, v85, v210
	v_or_b32_e32 v210, v142, v197
	v_mov_b32_e32 v211, v129
	v_mul_f32_e32 v81, v205, v81
	v_and_b32_e32 v210, -16, v210
	v_lshlrev_b64 v[210:211], 8, v[210:211]
	v_cvt_pk_bf16_f32 v84, v81, v84
	v_lshl_add_u64 v[210:211], s[20:21], 0, v[210:211]
	v_mov_b32_e32 v81, v153
	v_lshl_add_u64 v[210:211], v[210:211], 0, v[252:253]
	global_store_dwordx2 v[210:211], v[84:85], off offset:2560
	v_or_b32_e32 v210, v142, v195
	v_mov_b32_e32 v211, v129
	v_and_b32_e32 v210, -16, v210
	v_lshlrev_b64 v[210:211], 8, v[210:211]
	v_lshl_add_u64 v[210:211], s[20:21], 0, v[210:211]
	v_mul_f32_e32 v84, v205, v133
	v_mul_f32_e32 v85, v217, v216
	v_lshl_add_u64 v[210:211], v[210:211], 0, v[252:253]
	s_mov_b64 s[0:1], 0
	v_mul_f32_e32 v133, v222, v219
	v_mul_f32_e32 v205, v225, v224
	v_cvt_pk_bf16_f32 v84, v84, v85
	v_cvt_pk_bf16_f32 v85, v133, v205
	global_store_dwordx2 v[210:211], v[84:85], off offset:2560

.LBB0_236:
	v_lshl_add_u64 v[86:87], v[138:139], 2, s[8:9]
	v_subrev_u32_e32 v81, s8, v86
	v_and_b32_e32 v81, 0x3ff, v81
	ds_read_b32 v81, v81 offset:49152
	ds_read2_b32 v[226:227], v255 offset0:97 offset1:98
	ds_read_b32 v228, v255 offset:396
	v_bitop3_b32 v89, v136, s62, v167 bitop3:0xc8
	v_cvt_f32_u32_e32 v219, v89
	v_or_b32_e32 v97, 1, v89
	v_or_b32_e32 v105, 2, v89
	v_or_b32_e32 v133, 3, v89
	v_cvt_f32_u32_e32 v222, v97
	v_cvt_f32_u32_e32 v223, v105
	v_cvt_f32_u32_e32 v224, v133
	v_or_b32_e32 v82, v144, v89
	v_lshlrev_b32_e32 v89, 1, v89
	v_and_or_b32 v140, v89, s50, v128
	v_mul_f32_e32 v89, v218, v219
	v_fma_f32 v97, v219, v218, -v89
	v_floor_f32_e32 v89, v89
	v_mul_f32_e32 v105, v218, v222
	v_mul_f32_e32 v133, v218, v223
	v_mul_f32_e32 v216, v218, v224
	v_fma_f32 v89, v218, v219, -v89
	v_fma_f32 v217, v222, v218, -v105
	v_floor_f32_e32 v105, v105
	v_fma_f32 v225, v223, v218, -v133
	v_floor_f32_e32 v133, v133
	v_fma_f32 v229, v224, v218, -v216
	v_floor_f32_e32 v216, v216
	v_add_f32_e32 v89, v97, v89
	v_fma_f32 v97, v218, v222, -v105
	v_fma_f32 v105, v218, v223, -v133
	v_fma_f32 v133, v218, v224, -v216
	v_add_f32_e32 v97, v217, v97
	v_add_f32_e32 v105, v225, v105
	v_add_f32_e32 v133, v229, v133
	v_sin_f32_e32 v216, v89
	v_cos_f32_e32 v89, v89
	v_sin_f32_e32 v217, v97
	v_cos_f32_e32 v97, v97
	v_sin_f32_e32 v225, v105
	v_cos_f32_e32 v229, v105
	v_sin_f32_e32 v230, v133
	v_cos_f32_e32 v133, v133
	v_mov_b32_e32 v83, v145
	v_and_b32_e32 v113, 0x6c, v138
	v_bitop3_b32 v211, v138, s38, v173 bitop3:0x6c
	v_bitop3_b32 v210, v138, s48, v173 bitop3:0x6c
	v_bitop3_b32 v205, v138, s49, v173 bitop3:0x6c
	v_bitop3_b32 v141, v138, s42, v173 bitop3:0x6c
	v_lshlrev_b64 v[138:139], 9, v[82:83]
	s_mov_b64 s[0:1], -1
	s_and_b64 vcc, exec, s[4:5]
	v_lshl_add_u64 v[82:83], s[16:17], 0, v[138:139]
	s_waitcnt lgkmcnt(0)
	v_mul_f32_e32 v72, v72, v81
	s_waitcnt lgkmcnt(0)
	v_mul_f32_e32 v77, v77, v226
	v_mul_f32_e32 v73, v73, v226
	v_mul_f32_e32 v226, v78, v227
	v_mul_f32_e32 v74, v74, v227
	v_mul_f32_e32 v227, v79, v228
	v_mul_f32_e32 v79, v75, v228
	v_mul_f32_e32 v76, v76, v81
	v_mul_f32_e32 v105, v216, v72
	v_mul_f32_e32 v81, v89, v72
	v_mul_f32_e32 v72, v217, v73
	v_mul_f32_e32 v78, v97, v73
	v_mul_f32_e32 v73, v225, v74
	v_mul_f32_e32 v75, v229, v74
	v_mul_f32_e32 v228, v230, v79
	v_mul_f32_e32 v74, v133, v79
	v_fma_f32 v105, v89, v76, -v105
	v_fmac_f32_e32 v81, v216, v76
	v_fma_f32 v97, v97, v77, -v72
	v_fmac_f32_e32 v78, v217, v77
	v_fma_f32 v89, v229, v226, -v73
	v_fmac_f32_e32 v75, v225, v226
	v_fma_f32 v79, v133, v227, -v228
	v_fmac_f32_e32 v74, v230, v227
	v_lshlrev_b32_e32 v72, 1, v113
	s_cbranch_vccnz .LBB0_238
	v_mul_f32_e32 v73, 0x3d800000, v105
	v_mul_f32_e32 v216, 0x3d800000, v97
	v_bfe_u32 v76, v73, 16, 1
	v_bfe_u32 v217, v216, 16, 1
	v_add3_u32 v133, v73, v76, s47
	v_lshl_add_u64 v[76:77], v[82:83], 0, v[152:153]
	v_mul_f32_e32 v225, 0x3d800000, v78
	v_add3_u32 v217, v216, v217, s47
	global_store_short_d16_hi v[76:77], v217, off offset:512
	v_bfe_u32 v217, v225, 16, 1
	v_add3_u32 v217, v225, v217, s47
	global_store_short_d16_hi v[76:77], v217, off offset:544
	v_cvt_f32_ubyte0_e32 v217, v210
	v_mul_f32_e32 v217, v137, v217
	v_mul_f32_e32 v217, 0x3fb8aa3b, v217
	v_exp_f32_e32 v226, v217
	v_mul_f32_e32 v217, 0x3d800000, v89
	v_mul_f32_e32 v229, 0x3d800000, v79
	v_bfe_u32 v228, v217, 16, 1
	v_bfe_u32 v231, v229, 16, 1
	v_mul_f32_e32 v113, 0x3d800000, v81
	v_mul_f32_e32 v227, 0x3d800000, v75
	v_add3_u32 v228, v217, v228, s47
	v_mul_f32_e32 v230, 0x3d800000, v74
	v_add3_u32 v231, v229, v231, s47
	global_store_short_d16_hi v[76:77], v133, off
	v_bfe_u32 v133, v113, 16, 1
	global_store_short_d16_hi v[76:77], v228, off offset:1024
	v_bfe_u32 v228, v227, 16, 1
	global_store_short_d16_hi v[76:77], v231, off offset:1536
	v_bfe_u32 v231, v230, 16, 1
	v_add3_u32 v133, v113, v133, s47
	v_add3_u32 v228, v227, v228, s47
	v_add3_u32 v231, v230, v231, s47
	global_store_short_d16_hi v[76:77], v133, off offset:32
	global_store_short_d16_hi v[76:77], v228, off offset:1056
	v_cvt_f32_ubyte0_e32 v228, v205
	global_store_short_d16_hi v[76:77], v231, off offset:1568
	v_cvt_f32_ubyte0_e32 v76, v141
	v_mul_f32_e32 v228, v137, v228
	v_mul_f32_e32 v76, v137, v76
	v_cvt_f32_ubyte0_e32 v133, v211
	v_mul_f32_e32 v228, 0x3fb8aa3b, v228
	v_mul_f32_e32 v76, 0x3fb8aa3b, v76
	v_mul_f32_e32 v133, v137, v133
	v_exp_f32_e32 v228, v228
	v_exp_f32_e32 v231, v76
	v_mul_f32_e32 v133, 0x3fb8aa3b, v133
	v_exp_f32_e32 v133, v133
	v_mul_f32_e32 v76, v226, v216
	v_mul_f32_e32 v77, v228, v217
	v_mul_f32_e32 v216, v231, v229
	v_cvt_pk_bf16_f32 v77, v77, v216
	v_or_b32_e32 v216, v140, v197
	v_mov_b32_e32 v217, v129
	v_mul_f32_e32 v73, v133, v73
	v_and_b32_e32 v216, -16, v216
	v_lshlrev_b64 v[216:217], 8, v[216:217]
	v_cvt_pk_bf16_f32 v76, v73, v76
	v_lshl_add_u64 v[216:217], s[20:21], 0, v[216:217]
	v_mov_b32_e32 v73, v153
	v_lshl_add_u64 v[216:217], v[216:217], 0, v[252:253]
	global_store_dwordx2 v[216:217], v[76:77], off offset:3072
	v_or_b32_e32 v216, v140, v195
	v_mov_b32_e32 v217, v129
	v_and_b32_e32 v216, -16, v216
	v_lshlrev_b64 v[216:217], 8, v[216:217]
	v_lshl_add_u64 v[216:217], s[20:21], 0, v[216:217]
	v_mul_f32_e32 v76, v133, v113
	v_mul_f32_e32 v77, v226, v225
	v_lshl_add_u64 v[216:217], v[216:217], 0, v[252:253]
	s_mov_b64 s[0:1], 0
	v_mul_f32_e32 v113, v228, v227
	v_mul_f32_e32 v133, v231, v230
	v_cvt_pk_bf16_f32 v76, v76, v77
	v_cvt_pk_bf16_f32 v77, v113, v133
	global_store_dwordx2 v[216:217], v[76:77], off offset:3072

.LBB0_240:
	v_lshl_add_u64 v[78:79], v[134:135], 2, s[8:9]
	v_subrev_u32_e32 v73, s8, v78
	v_and_b32_e32 v73, 0x3ff, v73
	ds_read_b32 v73, v73 offset:49152
	ds_read2_b32 v[230:231], v255 offset0:113 offset1:114
	ds_read_b32 v232, v255 offset:460
	v_bitop3_b32 v74, v136, s63, v168 bitop3:0xc8
	v_cvt_f32_u32_e32 v225, v74
	v_or_b32_e32 v81, 1, v74
	v_or_b32_e32 v89, 2, v74
	v_or_b32_e32 v97, 3, v74
	v_cvt_f32_u32_e32 v226, v81
	v_cvt_f32_u32_e32 v227, v89
	v_cvt_f32_u32_e32 v228, v97
	v_or_b32_e32 v144, v144, v74
	v_lshlrev_b32_e32 v74, 1, v74
	v_mul_f32_e32 v81, v218, v225
	v_and_or_b32 v136, v74, s50, v128
	v_fma_f32 v89, v225, v218, -v81
	v_floor_f32_e32 v81, v81
	v_mul_f32_e32 v97, v218, v226
	v_mul_f32_e32 v113, v218, v227
	v_mul_f32_e32 v128, v218, v228
	v_and_b32_e32 v105, 0x7c, v134
	v_bitop3_b32 v75, v134, s42, v134 bitop3:0xc
	v_bitop3_b32 v217, v134, s38, v174 bitop3:0x6c
	v_bitop3_b32 v216, v134, s48, v174 bitop3:0x6c
	v_bitop3_b32 v139, v134, s49, v174 bitop3:0x6c
	v_lshlrev_b64 v[134:135], 9, v[144:145]
	v_fma_f32 v81, v218, v225, -v81
	v_fma_f32 v133, v226, v218, -v97
	v_floor_f32_e32 v97, v97
	v_fma_f32 v144, v227, v218, -v113
	v_floor_f32_e32 v113, v113
	v_fma_f32 v145, v228, v218, -v128
	v_floor_f32_e32 v128, v128
	v_add_f32_e32 v81, v89, v81
	v_fma_f32 v89, v218, v226, -v97
	v_fma_f32 v97, v218, v227, -v113
	v_fma_f32 v113, v218, v228, -v128
	v_add_f32_e32 v89, v133, v89
	v_add_f32_e32 v97, v144, v97
	v_add_f32_e32 v113, v145, v113
	v_sin_f32_e32 v128, v81
	v_cos_f32_e32 v81, v81
	v_sin_f32_e32 v133, v89
	v_cos_f32_e32 v89, v89
	v_sin_f32_e32 v144, v97
	v_cos_f32_e32 v145, v97
	v_sin_f32_e32 v218, v113
	v_cos_f32_e32 v113, v113
	s_mov_b64 s[0:1], -1
	s_and_b64 vcc, exec, s[4:5]
	v_cvt_f32_ubyte0_e32 v138, v75
	v_lshl_add_u64 v[74:75], s[16:17], 0, v[134:135]
	s_waitcnt lgkmcnt(0)
	v_mul_f32_e32 v64, v64, v73
	s_waitcnt lgkmcnt(0)
	v_mul_f32_e32 v65, v65, v230
	v_mul_f32_e32 v66, v66, v231
	v_mul_f32_e32 v67, v67, v232
	v_mul_f32_e32 v229, v68, v73
	v_mul_f32_e32 v233, v69, v230
	v_mul_f32_e32 v230, v70, v231
	v_mul_f32_e32 v231, v71, v232
	v_mul_f32_e32 v71, v128, v64
	v_mul_f32_e32 v73, v81, v64
	v_mul_f32_e32 v64, v133, v65
	v_mul_f32_e32 v70, v89, v65
	v_mul_f32_e32 v65, v144, v66
	v_mul_f32_e32 v69, v145, v66
	v_mul_f32_e32 v66, v218, v67
	v_mul_f32_e32 v68, v113, v67
	v_fma_f32 v97, v81, v229, -v71
	v_fmac_f32_e32 v73, v128, v229
	v_fma_f32 v89, v89, v233, -v64
	v_fmac_f32_e32 v70, v133, v233
	v_fma_f32 v81, v145, v230, -v65
	v_fmac_f32_e32 v69, v144, v230
	v_fma_f32 v71, v113, v231, -v66
	v_fmac_f32_e32 v68, v218, v231
	v_lshlrev_b32_e32 v64, 1, v105
	s_cbranch_vccnz .LBB0_242
	v_mul_f32_e32 v65, 0x3d800000, v97
	v_mul_f32_e32 v128, 0x3d800000, v89
	v_bfe_u32 v66, v65, 16, 1
	v_bfe_u32 v144, v128, 16, 1
	v_add3_u32 v113, v65, v66, s47
	v_lshl_add_u64 v[66:67], v[74:75], 0, v[152:153]
	v_mul_f32_e32 v133, 0x3d800000, v70
	v_add3_u32 v144, v128, v144, s47
	global_store_short_d16_hi v[66:67], v144, off offset:512
	v_bfe_u32 v144, v133, 16, 1
	v_add3_u32 v144, v133, v144, s47
	global_store_short_d16_hi v[66:67], v144, off offset:544
	v_cvt_f32_ubyte0_e32 v144, v216
	v_mul_f32_e32 v144, v137, v144
	v_mul_f32_e32 v144, 0x3fb8aa3b, v144
	v_exp_f32_e32 v218, v144
	v_mul_f32_e32 v144, 0x3d800000, v81
	v_bfe_u32 v145, v144, 16, 1
	v_mul_f32_e32 v229, 0x3d800000, v69
	v_add3_u32 v145, v144, v145, s47
	global_store_short_d16_hi v[66:67], v145, off offset:1024
	v_bfe_u32 v145, v229, 16, 1
	v_add3_u32 v145, v229, v145, s47
	global_store_short_d16_hi v[66:67], v145, off offset:1056
	v_cvt_f32_ubyte0_e32 v145, v139
	v_mul_f32_e32 v145, v137, v145
	v_mul_f32_e32 v145, 0x3fb8aa3b, v145
	v_exp_f32_e32 v230, v145
	v_mul_f32_e32 v145, 0x3d800000, v71
	v_bfe_u32 v232, v145, 16, 1
	v_mul_f32_e32 v105, 0x3d800000, v73
	v_mul_f32_e32 v231, 0x3d800000, v68
	v_add3_u32 v232, v145, v232, s47
	global_store_short_d16_hi v[66:67], v113, off
	v_bfe_u32 v113, v105, 16, 1
	global_store_short_d16_hi v[66:67], v232, off offset:1536
	v_bfe_u32 v232, v231, 16, 1
	v_add3_u32 v113, v105, v113, s47
	v_add3_u32 v232, v231, v232, s47
	global_store_short_d16_hi v[66:67], v113, off offset:32
	global_store_short_d16_hi v[66:67], v232, off offset:1568
	v_mul_f32_e32 v66, v137, v138
	v_cvt_f32_ubyte0_e32 v113, v217
	v_mul_f32_e32 v66, 0x3fb8aa3b, v66
	v_mul_f32_e32 v113, v137, v113
	v_exp_f32_e32 v232, v66
	v_mul_f32_e32 v113, 0x3fb8aa3b, v113
	v_exp_f32_e32 v113, v113
	v_mul_f32_e32 v66, v218, v128
	v_mul_f32_e32 v67, v230, v144
	v_mul_f32_e32 v128, v232, v145
	v_cvt_pk_bf16_f32 v67, v67, v128
	v_or_b32_e32 v128, v136, v197
	v_mul_f32_e32 v65, v113, v65
	v_and_b32_e32 v128, -16, v128
	v_lshlrev_b64 v[144:145], 8, v[128:129]
	v_cvt_pk_bf16_f32 v66, v65, v66
	v_lshl_add_u64 v[144:145], s[20:21], 0, v[144:145]
	v_mov_b32_e32 v65, v153
	v_lshl_add_u64 v[144:145], v[144:145], 0, v[252:253]
	v_or_b32_e32 v128, v136, v195
	global_store_dwordx2 v[144:145], v[66:67], off offset:3584
	v_and_b32_e32 v128, -16, v128
	v_lshlrev_b64 v[144:145], 8, v[128:129]
	v_lshl_add_u64 v[144:145], s[20:21], 0, v[144:145]
	v_mul_f32_e32 v66, v113, v105
	v_mul_f32_e32 v67, v218, v133
	v_lshl_add_u64 v[144:145], v[144:145], 0, v[252:253]
	s_mov_b64 s[0:1], 0
	v_mul_f32_e32 v105, v230, v229
	v_mul_f32_e32 v113, v232, v231
	v_cvt_pk_bf16_f32 v66, v66, v67
	v_cvt_pk_bf16_f32 v67, v105, v113
	global_store_dwordx2 v[144:145], v[66:67], off offset:3584

.LBB0_244:
	ds_read2_b32 v[230:231], v255 offset1:1
	ds_read2_b32 v[232:233], v255 offset0:2 offset1:3
	v_or_b32_e32 v65, 32, v154
	v_lshrrev_b32_e32 v68, 1, v65
	v_or_b32_e32 v68, v68, v158
	v_cvt_f32_ubyte0_e32 v68, v68
	v_mul_f32_e32 v69, 0xbdd49a78, v68
	v_cmp_gt_f32_e64 s[0:1], s43, v69
	v_or_b32_e32 v65, v65, v158
	s_mov_b64 s[26:27], -1
	v_cndmask_b32_e64 v69, 0, v169, s[0:1]
	v_fmac_f32_e32 v69, 0xbdd49a78, v68
	v_exp_f32_e32 v69, v69
	v_cndmask_b32_e64 v70, 0, v170, s[0:1]
	s_and_b64 vcc, exec, s[4:5]
	v_or_b32_e32 v68, 16, v65
	v_ldexp_f32 v69, v69, v70
	v_mul_f32_e32 v69, 0.15915494, v69
	v_mul_f32_e32 v70, v69, v160
	v_mul_f32_e32 v71, v69, v165
	v_mul_f32_e32 v73, v69, v178
	v_mul_f32_e32 v81, v69, v181
	v_fma_f32 v89, v160, v69, -v70
	v_floor_f32_e32 v70, v70
	v_fma_f32 v97, v165, v69, -v71
	v_floor_f32_e32 v71, v71
	v_fma_f32 v105, v178, v69, -v73
	v_floor_f32_e32 v73, v73
	v_fma_f32 v113, v181, v69, -v81
	v_floor_f32_e32 v81, v81
	v_fma_f32 v70, v69, v160, -v70
	v_fma_f32 v71, v69, v165, -v71
	v_fma_f32 v73, v69, v178, -v73
	v_fma_f32 v81, v69, v181, -v81
	v_add_f32_e32 v70, v89, v70
	v_add_f32_e32 v71, v97, v71
	v_add_f32_e32 v73, v105, v73
	v_add_f32_e32 v81, v113, v81
	v_sin_f32_e32 v89, v70
	v_cos_f32_e32 v70, v70
	v_sin_f32_e32 v97, v71
	v_cos_f32_e32 v71, v71
	v_sin_f32_e32 v105, v73
	v_cos_f32_e32 v73, v73
	v_sin_f32_e32 v113, v81
	v_cos_f32_e32 v81, v81
	v_add_lshl_u32 v152, v154, v158, 1
	s_waitcnt lgkmcnt(0)
	v_mul_f32_e32 v56, v56, v230
	v_mul_f32_e32 v57, v57, v231
	v_mul_f32_e32 v133, v62, v232
	v_mul_f32_e32 v62, v58, v232
	v_mul_f32_e32 v59, v59, v233
	v_mul_f32_e32 v128, v60, v230
	v_mul_f32_e32 v61, v61, v231
	v_mul_f32_e32 v134, v63, v233
	v_mul_f32_e32 v63, v89, v56
	v_mul_f32_e32 v60, v70, v56
	v_mul_f32_e32 v135, v97, v57
	v_mul_f32_e32 v58, v71, v57
	v_mul_f32_e32 v144, v105, v62
	v_mul_f32_e32 v57, v73, v62
	v_mul_f32_e32 v145, v113, v59
	v_mul_f32_e32 v56, v81, v59
	v_fma_f32 v63, v70, v128, -v63
	v_fmac_f32_e32 v60, v89, v128
	v_fma_f32 v62, v71, v61, -v135
	v_fmac_f32_e32 v58, v97, v61
	v_fma_f32 v61, v73, v133, -v144
	v_fmac_f32_e32 v57, v105, v133
	v_fma_f32 v59, v81, v134, -v145
	v_fmac_f32_e32 v56, v113, v134
	s_cbranch_vccnz .LBB0_246
	v_mul_f32_e32 v73, 0x3d800000, v63
	v_bfe_u32 v70, v73, 16, 1
	v_add3_u32 v89, v73, v70, s47
	v_lshl_add_u64 v[70:71], v[122:123], 0, v[152:153]
	v_mul_f32_e32 v122, 0x3d800000, v61
	v_bfe_u32 v123, v122, 16, 1
	v_mul_f32_e32 v134, 0x3d800000, v57
	v_add3_u32 v123, v122, v123, s47
	global_store_short_d16_hi v[70:71], v123, off offset:1088
	v_bfe_u32 v123, v134, 16, 1
	v_add3_u32 v123, v134, v123, s47
	global_store_short_d16_hi v[70:71], v123, off offset:1120
	v_mul_f32_e32 v123, v137, v164
	v_mul_f32_e32 v123, 0x3fb8aa3b, v123
	v_mul_f32_e32 v97, 0x3d800000, v62
	v_exp_f32_e32 v135, v123
	v_mul_f32_e32 v123, 0x3d800000, v59
	v_bfe_u32 v113, v97, 16, 1
	v_bfe_u32 v128, v123, 16, 1
	v_mul_f32_e32 v81, 0x3d800000, v60
	v_mul_f32_e32 v105, 0x3d800000, v58
	v_add3_u32 v113, v97, v113, s47
	v_mul_f32_e32 v144, 0x3d800000, v56
	v_add3_u32 v128, v123, v128, s47
	global_store_short_d16_hi v[70:71], v89, off offset:64
	v_bfe_u32 v89, v81, 16, 1
	global_store_short_d16_hi v[70:71], v113, off offset:576
	v_bfe_u32 v113, v105, 16, 1
	global_store_short_d16_hi v[70:71], v128, off offset:1600
	v_bfe_u32 v128, v144, 16, 1
	v_add3_u32 v89, v81, v89, s47
	v_add3_u32 v113, v105, v113, s47
	v_add3_u32 v128, v144, v128, s47
	global_store_short_d16_hi v[70:71], v89, off offset:96
	v_mul_f32_e32 v89, v137, v177
	global_store_short_d16_hi v[70:71], v113, off offset:608
	v_mul_f32_e32 v113, v137, v175
	global_store_short_d16_hi v[70:71], v128, off offset:1632
	v_mul_f32_e32 v70, v137, v162
	v_mul_f32_e32 v89, 0x3fb8aa3b, v89
	v_mul_f32_e32 v113, 0x3fb8aa3b, v113
	v_mul_f32_e32 v70, 0x3fb8aa3b, v70
	v_exp_f32_e32 v89, v89
	v_exp_f32_e32 v113, v113
	v_exp_f32_e32 v145, v70
	v_or_b32_e32 v128, v156, v65
	v_mul_f32_e32 v70, v89, v73
	v_mul_f32_e32 v71, v113, v97
	v_mul_f32_e32 v73, v135, v122
	v_mul_f32_e32 v97, v145, v123
	v_and_b32_e32 v128, -16, v128
	v_lshlrev_b64 v[122:123], 8, v[128:129]
	v_lshl_add_u64 v[122:123], s[20:21], 0, v[122:123]
	v_mov_b32_e32 v133, v153
	v_lshl_add_u64 v[122:123], v[122:123], 0, v[252:253]
	v_or_b32_e32 v128, v156, v68
	v_cvt_pk_bf16_f32 v70, v70, v71
	v_cvt_pk_bf16_f32 v71, v73, v97
	global_store_dwordx2 v[122:123], v[70:71], off
	v_and_b32_e32 v128, -16, v128
	v_lshlrev_b64 v[122:123], 8, v[128:129]
	v_lshl_add_u64 v[122:123], s[20:21], 0, v[122:123]
	v_mul_f32_e32 v70, v89, v81
	v_mul_f32_e32 v71, v113, v105
	v_lshl_add_u64 v[122:123], v[122:123], 0, v[252:253]
	s_mov_b64 s[26:27], 0
	v_mul_f32_e32 v73, v135, v134
	v_mul_f32_e32 v81, v145, v144
	v_cvt_pk_bf16_f32 v70, v70, v71
	v_cvt_pk_bf16_f32 v71, v73, v81
	global_store_dwordx2 v[122:123], v[70:71], off

.LBB0_248:
	v_subrev_u32_e32 v59, s8, v126
	v_and_b32_e32 v59, 0x3ff, v59
	ds_read_b32 v59, v59 offset:49152
	s_nop 0
	ds_read2_b32 v[56:57], v255 offset0:17 offset1:18
	ds_read_b32 v58, v255 offset:76
	v_mul_f32_e32 v60, v69, v183
	v_mul_f32_e32 v61, v69, v184
	v_mul_f32_e32 v62, v69, v185
	v_mul_f32_e32 v63, v69, v186
	v_fma_f32 v70, v183, v69, -v60
	v_floor_f32_e32 v60, v60
	v_fma_f32 v71, v184, v69, -v61
	v_floor_f32_e32 v61, v61
	v_fma_f32 v73, v185, v69, -v62
	v_floor_f32_e32 v62, v62
	v_fma_f32 v81, v186, v69, -v63
	v_floor_f32_e32 v63, v63
	v_fma_f32 v60, v69, v183, -v60
	v_fma_f32 v61, v69, v184, -v61
	v_fma_f32 v62, v69, v185, -v62
	v_fma_f32 v63, v69, v186, -v63
	v_add_f32_e32 v60, v70, v60
	v_add_f32_e32 v61, v71, v61
	v_add_f32_e32 v62, v73, v62
	v_add_f32_e32 v63, v81, v63
	v_sin_f32_e32 v70, v60
	v_cos_f32_e32 v60, v60
	v_sin_f32_e32 v71, v61
	v_cos_f32_e32 v61, v61
	v_sin_f32_e32 v73, v62
	v_cos_f32_e32 v62, v62
	v_sin_f32_e32 v81, v63
	v_cos_f32_e32 v63, v63
	s_and_b64 vcc, exec, s[4:5]
	s_mov_b64 s[0:1], -1
	s_waitcnt lgkmcnt(0)
	v_mul_f32_e32 v48, v48, v59
	s_waitcnt lgkmcnt(0)
	v_mul_f32_e32 v53, v53, v56
	v_mul_f32_e32 v49, v49, v56
	v_mul_f32_e32 v56, v54, v57
	v_mul_f32_e32 v54, v50, v57
	v_mul_f32_e32 v51, v51, v58
	v_mul_f32_e32 v89, v52, v59
	v_mul_f32_e32 v57, v55, v58
	v_mul_f32_e32 v55, v70, v48
	v_mul_f32_e32 v52, v60, v48
	v_mul_f32_e32 v58, v71, v49
	v_mul_f32_e32 v50, v61, v49
	v_mul_f32_e32 v59, v73, v54
	v_mul_f32_e32 v49, v62, v54
	v_mul_f32_e32 v97, v81, v51
	v_mul_f32_e32 v48, v63, v51
	v_fma_f32 v55, v60, v89, -v55
	v_fmac_f32_e32 v52, v70, v89
	v_fma_f32 v54, v61, v53, -v58
	v_fmac_f32_e32 v50, v71, v53
	v_fma_f32 v53, v62, v56, -v59
	v_fmac_f32_e32 v49, v73, v56
	v_fma_f32 v51, v63, v57, -v97
	v_fmac_f32_e32 v48, v81, v57
	s_cbranch_vccnz .LBB0_250
	v_mul_f32_e32 v58, 0x3d800000, v55
	v_bfe_u32 v56, v58, 16, 1
	v_mul_f32_e32 v60, 0x3d800000, v52
	v_add3_u32 v59, v58, v56, s47
	v_lshl_add_u64 v[56:57], v[120:121], 0, v[152:153]
	global_store_short_d16_hi v[56:57], v59, off offset:64
	v_bfe_u32 v59, v60, 16, 1
	v_add3_u32 v59, v60, v59, s47
	global_store_short_d16_hi v[56:57], v59, off offset:96
	v_cvt_f32_ubyte0_e32 v59, v163
	v_mul_f32_e32 v59, v137, v59
	v_mul_f32_e32 v59, 0x3fb8aa3b, v59
	v_exp_f32_e32 v61, v59
	v_mul_f32_e32 v59, 0x3d800000, v54
	v_mul_f32_e32 v70, 0x3d800000, v53
	v_mul_f32_e32 v81, 0x3d800000, v51
	v_bfe_u32 v63, v59, 16, 1
	v_bfe_u32 v73, v70, 16, 1
	v_bfe_u32 v97, v81, 16, 1
	v_mul_f32_e32 v62, 0x3d800000, v50
	v_add3_u32 v63, v59, v63, s47
	v_mul_f32_e32 v71, 0x3d800000, v49
	v_add3_u32 v73, v70, v73, s47
	v_mul_f32_e32 v89, 0x3d800000, v48
	v_add3_u32 v97, v81, v97, s47
	global_store_short_d16_hi v[56:57], v63, off offset:576
	v_bfe_u32 v63, v62, 16, 1
	global_store_short_d16_hi v[56:57], v73, off offset:1088
	v_bfe_u32 v73, v71, 16, 1
	global_store_short_d16_hi v[56:57], v97, off offset:1600
	v_bfe_u32 v97, v89, 16, 1
	v_add3_u32 v63, v62, v63, s47
	v_add3_u32 v73, v71, v73, s47
	v_add3_u32 v97, v89, v97, s47
	global_store_short_d16_hi v[56:57], v63, off offset:608
	v_cvt_f32_ubyte0_e32 v63, v161
	global_store_short_d16_hi v[56:57], v73, off offset:1120
	v_cvt_f32_ubyte0_e32 v73, v159
	global_store_short_d16_hi v[56:57], v97, off offset:1632
	v_cvt_f32_ubyte0_e32 v56, v157
	v_mul_f32_e32 v63, v137, v63
	v_mul_f32_e32 v73, v137, v73
	v_mul_f32_e32 v56, v137, v56
	v_mul_f32_e32 v63, 0x3fb8aa3b, v63
	v_mul_f32_e32 v73, 0x3fb8aa3b, v73
	v_mul_f32_e32 v56, 0x3fb8aa3b, v56
	v_exp_f32_e32 v63, v63
	v_exp_f32_e32 v73, v73
	v_exp_f32_e32 v97, v56
	v_mul_f32_e32 v56, v61, v58
	v_mul_f32_e32 v57, v63, v59
	v_mul_f32_e32 v58, v73, v70
	v_mul_f32_e32 v59, v97, v81
	v_or_b32_e32 v128, v155, v65
	v_cvt_pk_bf16_f32 v56, v56, v57
	v_cvt_pk_bf16_f32 v57, v58, v59
	v_and_b32_e32 v128, -16, v128
	v_lshlrev_b64 v[58:59], 8, v[128:129]
	v_lshl_add_u64 v[58:59], s[20:21], 0, v[58:59]
	v_mov_b32_e32 v113, v153
	v_lshl_add_u64 v[58:59], v[58:59], 0, v[252:253]
	global_store_dwordx2 v[58:59], v[56:57], off offset:512
	v_mul_f32_e32 v56, v61, v60
	v_mul_f32_e32 v57, v63, v62
	v_mul_f32_e32 v58, v73, v71
	v_mul_f32_e32 v59, v97, v89
	v_or_b32_e32 v128, v155, v68
	v_cvt_pk_bf16_f32 v56, v56, v57
	v_cvt_pk_bf16_f32 v57, v58, v59
	v_and_b32_e32 v128, -16, v128
	v_lshlrev_b64 v[58:59], 8, v[128:129]
	v_lshl_add_u64 v[58:59], s[20:21], 0, v[58:59]
	v_lshl_add_u64 v[58:59], v[58:59], 0, v[252:253]
	s_mov_b64 s[0:1], 0
	global_store_dwordx2 v[58:59], v[56:57], off offset:512

.LBB0_252:
	v_subrev_u32_e32 v51, s8, v118
	v_and_b32_e32 v51, 0x3ff, v51
	ds_read_b32 v51, v51 offset:49152
	s_nop 0
	ds_read2_b32 v[48:49], v255 offset0:33 offset1:34
	ds_read_b32 v50, v255 offset:140
	v_mul_f32_e32 v52, v69, v190
	v_mul_f32_e32 v53, v69, v191
	v_mul_f32_e32 v54, v69, v192
	v_mul_f32_e32 v55, v69, v193
	v_fma_f32 v56, v190, v69, -v52
	v_floor_f32_e32 v52, v52
	v_fma_f32 v57, v191, v69, -v53
	v_floor_f32_e32 v53, v53
	v_fma_f32 v58, v192, v69, -v54
	v_floor_f32_e32 v54, v54
	v_fma_f32 v59, v193, v69, -v55
	v_floor_f32_e32 v55, v55
	v_fma_f32 v52, v69, v190, -v52
	v_fma_f32 v53, v69, v191, -v53
	v_fma_f32 v54, v69, v192, -v54
	v_fma_f32 v55, v69, v193, -v55
	v_add_f32_e32 v52, v56, v52
	v_add_f32_e32 v53, v57, v53
	v_add_f32_e32 v54, v58, v54
	v_add_f32_e32 v55, v59, v55
	v_sin_f32_e32 v56, v52
	v_cos_f32_e32 v52, v52
	v_sin_f32_e32 v57, v53
	v_cos_f32_e32 v53, v53
	v_sin_f32_e32 v58, v54
	v_cos_f32_e32 v54, v54
	v_sin_f32_e32 v59, v55
	v_cos_f32_e32 v55, v55
	s_and_b64 vcc, exec, s[4:5]
	s_mov_b64 s[0:1], -1
	s_waitcnt lgkmcnt(0)
	v_mul_f32_e32 v40, v40, v51
	s_waitcnt lgkmcnt(0)
	v_mul_f32_e32 v45, v45, v48
	v_mul_f32_e32 v41, v41, v48
	v_mul_f32_e32 v48, v46, v49
	v_mul_f32_e32 v46, v42, v49
	v_mul_f32_e32 v43, v43, v50
	v_mul_f32_e32 v60, v44, v51
	v_mul_f32_e32 v49, v47, v50
	v_mul_f32_e32 v47, v56, v40
	v_mul_f32_e32 v44, v52, v40
	v_mul_f32_e32 v50, v57, v41
	v_mul_f32_e32 v42, v53, v41
	v_mul_f32_e32 v51, v58, v46
	v_mul_f32_e32 v41, v54, v46
	v_mul_f32_e32 v61, v59, v43
	v_mul_f32_e32 v40, v55, v43
	v_fma_f32 v47, v52, v60, -v47
	v_fmac_f32_e32 v44, v56, v60
	v_fma_f32 v46, v53, v45, -v50
	v_fmac_f32_e32 v42, v57, v45
	v_fma_f32 v45, v54, v48, -v51
	v_fmac_f32_e32 v41, v58, v48
	v_fma_f32 v43, v55, v49, -v61
	v_fmac_f32_e32 v40, v59, v49
	s_cbranch_vccnz .LBB0_254
	v_mul_f32_e32 v50, 0x3d800000, v47
	v_bfe_u32 v48, v50, 16, 1
	v_mul_f32_e32 v52, 0x3d800000, v44
	v_add3_u32 v51, v50, v48, s47
	v_lshl_add_u64 v[48:49], v[114:115], 0, v[152:153]
	global_store_short_d16_hi v[48:49], v51, off offset:64
	v_bfe_u32 v51, v52, 16, 1
	v_add3_u32 v51, v52, v51, s47
	global_store_short_d16_hi v[48:49], v51, off offset:96
	v_cvt_f32_ubyte0_e32 v51, v180
	v_mul_f32_e32 v51, v137, v51
	v_mul_f32_e32 v51, 0x3fb8aa3b, v51
	v_exp_f32_e32 v53, v51
	v_mul_f32_e32 v51, 0x3d800000, v46
	v_mul_f32_e32 v56, 0x3d800000, v45
	v_mul_f32_e32 v59, 0x3d800000, v43
	v_bfe_u32 v55, v51, 16, 1
	v_bfe_u32 v58, v56, 16, 1
	v_bfe_u32 v61, v59, 16, 1
	v_mul_f32_e32 v54, 0x3d800000, v42
	v_add3_u32 v55, v51, v55, s47
	v_mul_f32_e32 v57, 0x3d800000, v41
	v_add3_u32 v58, v56, v58, s47
	v_mul_f32_e32 v60, 0x3d800000, v40
	v_add3_u32 v61, v59, v61, s47
	global_store_short_d16_hi v[48:49], v55, off offset:576
	v_bfe_u32 v55, v54, 16, 1
	global_store_short_d16_hi v[48:49], v58, off offset:1088
	v_bfe_u32 v58, v57, 16, 1
	global_store_short_d16_hi v[48:49], v61, off offset:1600
	v_bfe_u32 v61, v60, 16, 1
	v_add3_u32 v55, v54, v55, s47
	v_add3_u32 v58, v57, v58, s47
	v_add3_u32 v61, v60, v61, s47
	global_store_short_d16_hi v[48:49], v55, off offset:608
	v_cvt_f32_ubyte0_e32 v55, v179
	global_store_short_d16_hi v[48:49], v58, off offset:1120
	v_cvt_f32_ubyte0_e32 v58, v176
	global_store_short_d16_hi v[48:49], v61, off offset:1632
	v_cvt_f32_ubyte0_e32 v48, v151
	v_mul_f32_e32 v55, v137, v55
	v_mul_f32_e32 v58, v137, v58
	v_mul_f32_e32 v48, v137, v48
	v_mul_f32_e32 v55, 0x3fb8aa3b, v55
	v_mul_f32_e32 v58, 0x3fb8aa3b, v58
	v_mul_f32_e32 v48, 0x3fb8aa3b, v48
	v_exp_f32_e32 v55, v55
	v_exp_f32_e32 v58, v58
	v_exp_f32_e32 v61, v48
	v_mul_f32_e32 v48, v53, v50
	v_mul_f32_e32 v49, v55, v51
	v_mul_f32_e32 v50, v58, v56
	v_mul_f32_e32 v51, v61, v59
	v_or_b32_e32 v128, v150, v65
	v_cvt_pk_bf16_f32 v48, v48, v49
	v_cvt_pk_bf16_f32 v49, v50, v51
	v_and_b32_e32 v128, -16, v128
	v_lshlrev_b64 v[50:51], 8, v[128:129]
	v_lshl_add_u64 v[50:51], s[20:21], 0, v[50:51]
	v_mov_b32_e32 v105, v153
	v_lshl_add_u64 v[50:51], v[50:51], 0, v[252:253]
	global_store_dwordx2 v[50:51], v[48:49], off offset:1024
	v_mul_f32_e32 v48, v53, v52
	v_mul_f32_e32 v49, v55, v54
	v_mul_f32_e32 v50, v58, v57
	v_mul_f32_e32 v51, v61, v60
	v_or_b32_e32 v128, v150, v68
	v_cvt_pk_bf16_f32 v48, v48, v49
	v_cvt_pk_bf16_f32 v49, v50, v51
	v_and_b32_e32 v128, -16, v128
	v_lshlrev_b64 v[50:51], 8, v[128:129]
	v_lshl_add_u64 v[50:51], s[20:21], 0, v[50:51]
	v_lshl_add_u64 v[50:51], v[50:51], 0, v[252:253]
	s_mov_b64 s[0:1], 0
	global_store_dwordx2 v[50:51], v[48:49], off offset:1024

.LBB0_256:
	v_subrev_u32_e32 v43, s8, v110
	v_and_b32_e32 v43, 0x3ff, v43
	ds_read_b32 v43, v43 offset:49152
	s_nop 0
	ds_read2_b32 v[40:41], v255 offset0:49 offset1:50
	ds_read_b32 v42, v255 offset:204
	v_mul_f32_e32 v44, v69, v199
	v_mul_f32_e32 v45, v69, v200
	v_mul_f32_e32 v46, v69, v201
	v_mul_f32_e32 v47, v69, v202
	v_fma_f32 v48, v199, v69, -v44
	v_floor_f32_e32 v44, v44
	v_fma_f32 v49, v200, v69, -v45
	v_floor_f32_e32 v45, v45
	v_fma_f32 v50, v201, v69, -v46
	v_floor_f32_e32 v46, v46
	v_fma_f32 v51, v202, v69, -v47
	v_floor_f32_e32 v47, v47
	v_fma_f32 v44, v69, v199, -v44
	v_fma_f32 v45, v69, v200, -v45
	v_fma_f32 v46, v69, v201, -v46
	v_fma_f32 v47, v69, v202, -v47
	v_add_f32_e32 v44, v48, v44
	v_add_f32_e32 v45, v49, v45
	v_add_f32_e32 v46, v50, v46
	v_add_f32_e32 v47, v51, v47
	v_sin_f32_e32 v48, v44
	v_cos_f32_e32 v44, v44
	v_sin_f32_e32 v49, v45
	v_cos_f32_e32 v45, v45
	v_sin_f32_e32 v50, v46
	v_cos_f32_e32 v46, v46
	v_sin_f32_e32 v51, v47
	v_cos_f32_e32 v47, v47
	s_and_b64 vcc, exec, s[4:5]
	s_mov_b64 s[0:1], -1
	s_waitcnt lgkmcnt(0)
	v_mul_f32_e32 v32, v32, v43
	s_waitcnt lgkmcnt(0)
	v_mul_f32_e32 v37, v37, v40
	v_mul_f32_e32 v33, v33, v40
	v_mul_f32_e32 v40, v38, v41
	v_mul_f32_e32 v38, v34, v41
	v_mul_f32_e32 v35, v35, v42
	v_mul_f32_e32 v52, v36, v43
	v_mul_f32_e32 v41, v39, v42
	v_mul_f32_e32 v39, v48, v32
	v_mul_f32_e32 v36, v44, v32
	v_mul_f32_e32 v42, v49, v33
	v_mul_f32_e32 v34, v45, v33
	v_mul_f32_e32 v43, v50, v38
	v_mul_f32_e32 v33, v46, v38
	v_mul_f32_e32 v53, v51, v35
	v_mul_f32_e32 v32, v47, v35
	v_fma_f32 v39, v44, v52, -v39
	v_fmac_f32_e32 v36, v48, v52
	v_fma_f32 v38, v45, v37, -v42
	v_fmac_f32_e32 v34, v49, v37
	v_fma_f32 v37, v46, v40, -v43
	v_fmac_f32_e32 v33, v50, v40
	v_fma_f32 v35, v47, v41, -v53
	v_fmac_f32_e32 v32, v51, v41
	s_cbranch_vccnz .LBB0_258
	v_mul_f32_e32 v42, 0x3d800000, v39
	v_bfe_u32 v40, v42, 16, 1
	v_mul_f32_e32 v44, 0x3d800000, v36
	v_add3_u32 v43, v42, v40, s47
	v_lshl_add_u64 v[40:41], v[106:107], 0, v[152:153]
	global_store_short_d16_hi v[40:41], v43, off offset:64
	v_bfe_u32 v43, v44, 16, 1
	v_add3_u32 v43, v44, v43, s47
	global_store_short_d16_hi v[40:41], v43, off offset:96
	v_cvt_f32_ubyte0_e32 v43, v188
	v_mul_f32_e32 v43, v137, v43
	v_mul_f32_e32 v43, 0x3fb8aa3b, v43
	v_exp_f32_e32 v45, v43
	v_mul_f32_e32 v43, 0x3d800000, v38
	v_mul_f32_e32 v48, 0x3d800000, v37
	v_mul_f32_e32 v51, 0x3d800000, v35
	v_bfe_u32 v47, v43, 16, 1
	v_bfe_u32 v50, v48, 16, 1
	v_bfe_u32 v53, v51, 16, 1
	v_mul_f32_e32 v46, 0x3d800000, v34
	v_add3_u32 v47, v43, v47, s47
	v_mul_f32_e32 v49, 0x3d800000, v33
	v_add3_u32 v50, v48, v50, s47
	v_mul_f32_e32 v52, 0x3d800000, v32
	v_add3_u32 v53, v51, v53, s47
	global_store_short_d16_hi v[40:41], v47, off offset:576
	v_bfe_u32 v47, v46, 16, 1
	global_store_short_d16_hi v[40:41], v50, off offset:1088
	v_bfe_u32 v50, v49, 16, 1
	global_store_short_d16_hi v[40:41], v53, off offset:1600
	v_bfe_u32 v53, v52, 16, 1
	v_add3_u32 v47, v46, v47, s47
	v_add3_u32 v50, v49, v50, s47
	v_add3_u32 v53, v52, v53, s47
	global_store_short_d16_hi v[40:41], v47, off offset:608
	v_cvt_f32_ubyte0_e32 v47, v187
	global_store_short_d16_hi v[40:41], v50, off offset:1120
	v_cvt_f32_ubyte0_e32 v50, v182
	global_store_short_d16_hi v[40:41], v53, off offset:1632
	v_cvt_f32_ubyte0_e32 v40, v149
	v_mul_f32_e32 v47, v137, v47
	v_mul_f32_e32 v50, v137, v50
	v_mul_f32_e32 v40, v137, v40
	v_mul_f32_e32 v47, 0x3fb8aa3b, v47
	v_mul_f32_e32 v50, 0x3fb8aa3b, v50
	v_mul_f32_e32 v40, 0x3fb8aa3b, v40
	v_exp_f32_e32 v47, v47
	v_exp_f32_e32 v50, v50
	v_exp_f32_e32 v53, v40
	v_mul_f32_e32 v40, v45, v42
	v_mul_f32_e32 v41, v47, v43
	v_mul_f32_e32 v42, v50, v48
	v_mul_f32_e32 v43, v53, v51
	v_or_b32_e32 v128, v148, v65
	v_cvt_pk_bf16_f32 v40, v40, v41
	v_cvt_pk_bf16_f32 v41, v42, v43
	v_and_b32_e32 v128, -16, v128
	v_lshlrev_b64 v[42:43], 8, v[128:129]
	v_lshl_add_u64 v[42:43], s[20:21], 0, v[42:43]
	v_mov_b32_e32 v97, v153
	v_lshl_add_u64 v[42:43], v[42:43], 0, v[252:253]
	global_store_dwordx2 v[42:43], v[40:41], off offset:1536
	v_mul_f32_e32 v40, v45, v44
	v_mul_f32_e32 v41, v47, v46
	v_mul_f32_e32 v42, v50, v49
	v_mul_f32_e32 v43, v53, v52
	v_or_b32_e32 v128, v148, v68
	v_cvt_pk_bf16_f32 v40, v40, v41
	v_cvt_pk_bf16_f32 v41, v42, v43
	v_and_b32_e32 v128, -16, v128
	v_lshlrev_b64 v[42:43], 8, v[128:129]
	v_lshl_add_u64 v[42:43], s[20:21], 0, v[42:43]
	v_lshl_add_u64 v[42:43], v[42:43], 0, v[252:253]
	s_mov_b64 s[0:1], 0
	global_store_dwordx2 v[42:43], v[40:41], off offset:1536

.LBB0_260:
	v_subrev_u32_e32 v35, s8, v102
	v_and_b32_e32 v35, 0x3ff, v35
	ds_read_b32 v35, v35 offset:49152
	s_nop 0
	ds_read2_b32 v[32:33], v255 offset0:65 offset1:66
	ds_read_b32 v34, v255 offset:268
	v_mul_f32_e32 v36, v69, v206
	v_mul_f32_e32 v37, v69, v207
	v_mul_f32_e32 v38, v69, v208
	v_mul_f32_e32 v39, v69, v209
	v_fma_f32 v40, v206, v69, -v36
	v_floor_f32_e32 v36, v36
	v_fma_f32 v41, v207, v69, -v37
	v_floor_f32_e32 v37, v37
	v_fma_f32 v42, v208, v69, -v38
	v_floor_f32_e32 v38, v38
	v_fma_f32 v43, v209, v69, -v39
	v_floor_f32_e32 v39, v39
	v_fma_f32 v36, v69, v206, -v36
	v_fma_f32 v37, v69, v207, -v37
	v_fma_f32 v38, v69, v208, -v38
	v_fma_f32 v39, v69, v209, -v39
	v_add_f32_e32 v36, v40, v36
	v_add_f32_e32 v37, v41, v37
	v_add_f32_e32 v38, v42, v38
	v_add_f32_e32 v39, v43, v39
	v_sin_f32_e32 v40, v36
	v_cos_f32_e32 v36, v36
	v_sin_f32_e32 v41, v37
	v_cos_f32_e32 v37, v37
	v_sin_f32_e32 v42, v38
	v_cos_f32_e32 v38, v38
	v_sin_f32_e32 v43, v39
	v_cos_f32_e32 v39, v39
	s_and_b64 vcc, exec, s[4:5]
	s_mov_b64 s[0:1], -1
	s_waitcnt lgkmcnt(0)
	v_mul_f32_e32 v24, v24, v35
	s_waitcnt lgkmcnt(0)
	v_mul_f32_e32 v29, v29, v32
	v_mul_f32_e32 v25, v25, v32
	v_mul_f32_e32 v32, v30, v33
	v_mul_f32_e32 v30, v26, v33
	v_mul_f32_e32 v27, v27, v34
	v_mul_f32_e32 v44, v28, v35
	v_mul_f32_e32 v33, v31, v34
	v_mul_f32_e32 v31, v40, v24
	v_mul_f32_e32 v28, v36, v24
	v_mul_f32_e32 v34, v41, v25
	v_mul_f32_e32 v26, v37, v25
	v_mul_f32_e32 v35, v42, v30
	v_mul_f32_e32 v25, v38, v30
	v_mul_f32_e32 v45, v43, v27
	v_mul_f32_e32 v24, v39, v27
	v_fma_f32 v31, v36, v44, -v31
	v_fmac_f32_e32 v28, v40, v44
	v_fma_f32 v30, v37, v29, -v34
	v_fmac_f32_e32 v26, v41, v29
	v_fma_f32 v29, v38, v32, -v35
	v_fmac_f32_e32 v25, v42, v32
	v_fma_f32 v27, v39, v33, -v45
	v_fmac_f32_e32 v24, v43, v33
	s_cbranch_vccnz .LBB0_262
	v_mul_f32_e32 v34, 0x3d800000, v31
	v_bfe_u32 v32, v34, 16, 1
	v_mul_f32_e32 v36, 0x3d800000, v28
	v_add3_u32 v35, v34, v32, s47
	v_lshl_add_u64 v[32:33], v[98:99], 0, v[152:153]
	global_store_short_d16_hi v[32:33], v35, off offset:64
	v_bfe_u32 v35, v36, 16, 1
	v_add3_u32 v35, v36, v35, s47
	global_store_short_d16_hi v[32:33], v35, off offset:96
	v_cvt_f32_ubyte0_e32 v35, v196
	v_mul_f32_e32 v35, v137, v35
	v_mul_f32_e32 v35, 0x3fb8aa3b, v35
	v_exp_f32_e32 v37, v35
	v_mul_f32_e32 v35, 0x3d800000, v30
	v_mul_f32_e32 v40, 0x3d800000, v29
	v_mul_f32_e32 v43, 0x3d800000, v27
	v_bfe_u32 v39, v35, 16, 1
	v_bfe_u32 v42, v40, 16, 1
	v_bfe_u32 v45, v43, 16, 1
	v_mul_f32_e32 v38, 0x3d800000, v26
	v_add3_u32 v39, v35, v39, s47
	v_mul_f32_e32 v41, 0x3d800000, v25
	v_add3_u32 v42, v40, v42, s47
	v_mul_f32_e32 v44, 0x3d800000, v24
	v_add3_u32 v45, v43, v45, s47
	global_store_short_d16_hi v[32:33], v39, off offset:576
	v_bfe_u32 v39, v38, 16, 1
	global_store_short_d16_hi v[32:33], v42, off offset:1088
	v_bfe_u32 v42, v41, 16, 1
	global_store_short_d16_hi v[32:33], v45, off offset:1600
	v_bfe_u32 v45, v44, 16, 1
	v_add3_u32 v39, v38, v39, s47
	v_add3_u32 v42, v41, v42, s47
	v_add3_u32 v45, v44, v45, s47
	global_store_short_d16_hi v[32:33], v39, off offset:608
	v_cvt_f32_ubyte0_e32 v39, v194
	global_store_short_d16_hi v[32:33], v42, off offset:1120
	v_cvt_f32_ubyte0_e32 v42, v189
	global_store_short_d16_hi v[32:33], v45, off offset:1632
	v_cvt_f32_ubyte0_e32 v32, v147
	v_mul_f32_e32 v39, v137, v39
	v_mul_f32_e32 v42, v137, v42
	v_mul_f32_e32 v32, v137, v32
	v_mul_f32_e32 v39, 0x3fb8aa3b, v39
	v_mul_f32_e32 v42, 0x3fb8aa3b, v42
	v_mul_f32_e32 v32, 0x3fb8aa3b, v32
	v_exp_f32_e32 v39, v39
	v_exp_f32_e32 v42, v42
	v_exp_f32_e32 v45, v32
	v_mul_f32_e32 v32, v37, v34
	v_mul_f32_e32 v33, v39, v35
	v_mul_f32_e32 v34, v42, v40
	v_mul_f32_e32 v35, v45, v43
	v_or_b32_e32 v128, v146, v65
	v_cvt_pk_bf16_f32 v32, v32, v33
	v_cvt_pk_bf16_f32 v33, v34, v35
	v_and_b32_e32 v128, -16, v128
	v_lshlrev_b64 v[34:35], 8, v[128:129]
	v_lshl_add_u64 v[34:35], s[20:21], 0, v[34:35]
	v_mov_b32_e32 v89, v153
	v_lshl_add_u64 v[34:35], v[34:35], 0, v[252:253]
	global_store_dwordx2 v[34:35], v[32:33], off offset:2048
	v_mul_f32_e32 v32, v37, v36
	v_mul_f32_e32 v33, v39, v38
	v_mul_f32_e32 v34, v42, v41
	v_mul_f32_e32 v35, v45, v44
	v_or_b32_e32 v128, v146, v68
	v_cvt_pk_bf16_f32 v32, v32, v33
	v_cvt_pk_bf16_f32 v33, v34, v35
	v_and_b32_e32 v128, -16, v128
	v_lshlrev_b64 v[34:35], 8, v[128:129]
	v_lshl_add_u64 v[34:35], s[20:21], 0, v[34:35]
	v_lshl_add_u64 v[34:35], v[34:35], 0, v[252:253]
	s_mov_b64 s[0:1], 0
	global_store_dwordx2 v[34:35], v[32:33], off offset:2048

.LBB0_264:
	v_subrev_u32_e32 v27, s8, v94
	v_and_b32_e32 v27, 0x3ff, v27
	ds_read_b32 v27, v27 offset:49152
	s_nop 0
	ds_read2_b32 v[24:25], v255 offset0:81 offset1:82
	ds_read_b32 v26, v255 offset:332
	v_mul_f32_e32 v28, v69, v212
	v_mul_f32_e32 v29, v69, v213
	v_mul_f32_e32 v30, v69, v214
	v_mul_f32_e32 v31, v69, v215
	v_fma_f32 v32, v212, v69, -v28
	v_floor_f32_e32 v28, v28
	v_fma_f32 v33, v213, v69, -v29
	v_floor_f32_e32 v29, v29
	v_fma_f32 v34, v214, v69, -v30
	v_floor_f32_e32 v30, v30
	v_fma_f32 v35, v215, v69, -v31
	v_floor_f32_e32 v31, v31
	v_fma_f32 v28, v69, v212, -v28
	v_fma_f32 v29, v69, v213, -v29
	v_fma_f32 v30, v69, v214, -v30
	v_fma_f32 v31, v69, v215, -v31
	v_add_f32_e32 v28, v32, v28
	v_add_f32_e32 v29, v33, v29
	v_add_f32_e32 v30, v34, v30
	v_add_f32_e32 v31, v35, v31
	v_sin_f32_e32 v32, v28
	v_cos_f32_e32 v28, v28
	v_sin_f32_e32 v33, v29
	v_cos_f32_e32 v29, v29
	v_sin_f32_e32 v34, v30
	v_cos_f32_e32 v30, v30
	v_sin_f32_e32 v35, v31
	v_cos_f32_e32 v31, v31
	s_and_b64 vcc, exec, s[4:5]
	s_mov_b64 s[0:1], -1
	s_waitcnt lgkmcnt(0)
	v_mul_f32_e32 v16, v16, v27
	s_waitcnt lgkmcnt(0)
	v_mul_f32_e32 v21, v21, v24
	v_mul_f32_e32 v17, v17, v24
	v_mul_f32_e32 v24, v22, v25
	v_mul_f32_e32 v22, v18, v25
	v_mul_f32_e32 v19, v19, v26
	v_mul_f32_e32 v36, v20, v27
	v_mul_f32_e32 v25, v23, v26
	v_mul_f32_e32 v23, v32, v16
	v_mul_f32_e32 v20, v28, v16
	v_mul_f32_e32 v26, v33, v17
	v_mul_f32_e32 v18, v29, v17
	v_mul_f32_e32 v27, v34, v22
	v_mul_f32_e32 v17, v30, v22
	v_mul_f32_e32 v37, v35, v19
	v_mul_f32_e32 v16, v31, v19
	v_fma_f32 v23, v28, v36, -v23
	v_fmac_f32_e32 v20, v32, v36
	v_fma_f32 v22, v29, v21, -v26
	v_fmac_f32_e32 v18, v33, v21
	v_fma_f32 v21, v30, v24, -v27
	v_fmac_f32_e32 v17, v34, v24
	v_fma_f32 v19, v31, v25, -v37
	v_fmac_f32_e32 v16, v35, v25
	s_cbranch_vccnz .LBB0_266
	v_mul_f32_e32 v26, 0x3d800000, v23
	v_bfe_u32 v24, v26, 16, 1
	v_mul_f32_e32 v28, 0x3d800000, v20
	v_add3_u32 v27, v26, v24, s47
	v_lshl_add_u64 v[24:25], v[90:91], 0, v[152:153]
	global_store_short_d16_hi v[24:25], v27, off offset:64
	v_bfe_u32 v27, v28, 16, 1
	v_add3_u32 v27, v28, v27, s47
	global_store_short_d16_hi v[24:25], v27, off offset:96
	v_cvt_f32_ubyte0_e32 v27, v204
	v_mul_f32_e32 v27, v137, v27
	v_mul_f32_e32 v27, 0x3fb8aa3b, v27
	v_exp_f32_e32 v29, v27
	v_mul_f32_e32 v27, 0x3d800000, v22
	v_mul_f32_e32 v32, 0x3d800000, v21
	v_mul_f32_e32 v35, 0x3d800000, v19
	v_bfe_u32 v31, v27, 16, 1
	v_bfe_u32 v34, v32, 16, 1
	v_bfe_u32 v37, v35, 16, 1
	v_mul_f32_e32 v30, 0x3d800000, v18
	v_add3_u32 v31, v27, v31, s47
	v_mul_f32_e32 v33, 0x3d800000, v17
	v_add3_u32 v34, v32, v34, s47
	v_mul_f32_e32 v36, 0x3d800000, v16
	v_add3_u32 v37, v35, v37, s47
	global_store_short_d16_hi v[24:25], v31, off offset:576
	v_bfe_u32 v31, v30, 16, 1
	global_store_short_d16_hi v[24:25], v34, off offset:1088
	v_bfe_u32 v34, v33, 16, 1
	global_store_short_d16_hi v[24:25], v37, off offset:1600
	v_bfe_u32 v37, v36, 16, 1
	v_add3_u32 v31, v30, v31, s47
	v_add3_u32 v34, v33, v34, s47
	v_add3_u32 v37, v36, v37, s47
	global_store_short_d16_hi v[24:25], v31, off offset:608
	v_cvt_f32_ubyte0_e32 v31, v203
	global_store_short_d16_hi v[24:25], v34, off offset:1120
	v_cvt_f32_ubyte0_e32 v34, v198
	global_store_short_d16_hi v[24:25], v37, off offset:1632
	v_cvt_f32_ubyte0_e32 v24, v143
	v_mul_f32_e32 v31, v137, v31
	v_mul_f32_e32 v34, v137, v34
	v_mul_f32_e32 v24, v137, v24
	v_mul_f32_e32 v31, 0x3fb8aa3b, v31
	v_mul_f32_e32 v34, 0x3fb8aa3b, v34
	v_mul_f32_e32 v24, 0x3fb8aa3b, v24
	v_exp_f32_e32 v31, v31
	v_exp_f32_e32 v34, v34
	v_exp_f32_e32 v37, v24
	v_mul_f32_e32 v24, v29, v26
	v_mul_f32_e32 v25, v31, v27
	v_mul_f32_e32 v26, v34, v32
	v_mul_f32_e32 v27, v37, v35
	v_or_b32_e32 v128, v142, v65
	v_cvt_pk_bf16_f32 v24, v24, v25
	v_cvt_pk_bf16_f32 v25, v26, v27
	v_and_b32_e32 v128, -16, v128
	v_lshlrev_b64 v[26:27], 8, v[128:129]
	v_lshl_add_u64 v[26:27], s[20:21], 0, v[26:27]
	v_mov_b32_e32 v81, v153
	v_lshl_add_u64 v[26:27], v[26:27], 0, v[252:253]
	global_store_dwordx2 v[26:27], v[24:25], off offset:2560
	v_mul_f32_e32 v24, v29, v28
	v_mul_f32_e32 v25, v31, v30
	v_mul_f32_e32 v26, v34, v33
	v_mul_f32_e32 v27, v37, v36
	v_or_b32_e32 v128, v142, v68
	v_cvt_pk_bf16_f32 v24, v24, v25
	v_cvt_pk_bf16_f32 v25, v26, v27
	v_and_b32_e32 v128, -16, v128
	v_lshlrev_b64 v[26:27], 8, v[128:129]
	v_lshl_add_u64 v[26:27], s[20:21], 0, v[26:27]
	v_lshl_add_u64 v[26:27], v[26:27], 0, v[252:253]
	s_mov_b64 s[0:1], 0
	global_store_dwordx2 v[26:27], v[24:25], off offset:2560

.LBB0_268:
	v_subrev_u32_e32 v19, s8, v86
	v_and_b32_e32 v19, 0x3ff, v19
	ds_read_b32 v19, v19 offset:49152
	s_nop 0
	ds_read2_b32 v[16:17], v255 offset0:97 offset1:98
	ds_read_b32 v18, v255 offset:396
	v_mul_f32_e32 v20, v69, v219
	v_mul_f32_e32 v21, v69, v222
	v_mul_f32_e32 v22, v69, v223
	v_mul_f32_e32 v23, v69, v224
	v_fma_f32 v24, v219, v69, -v20
	v_floor_f32_e32 v20, v20
	v_fma_f32 v25, v222, v69, -v21
	v_floor_f32_e32 v21, v21
	v_fma_f32 v26, v223, v69, -v22
	v_floor_f32_e32 v22, v22
	v_fma_f32 v27, v224, v69, -v23
	v_floor_f32_e32 v23, v23
	v_fma_f32 v20, v69, v219, -v20
	v_fma_f32 v21, v69, v222, -v21
	v_fma_f32 v22, v69, v223, -v22
	v_fma_f32 v23, v69, v224, -v23
	v_add_f32_e32 v20, v24, v20
	v_add_f32_e32 v21, v25, v21
	v_add_f32_e32 v22, v26, v22
	v_add_f32_e32 v23, v27, v23
	v_sin_f32_e32 v24, v20
	v_cos_f32_e32 v20, v20
	v_sin_f32_e32 v25, v21
	v_cos_f32_e32 v21, v21
	v_sin_f32_e32 v26, v22
	v_cos_f32_e32 v22, v22
	v_sin_f32_e32 v27, v23
	v_cos_f32_e32 v23, v23
	s_and_b64 vcc, exec, s[4:5]
	s_mov_b64 s[0:1], -1
	s_waitcnt lgkmcnt(0)
	v_mul_f32_e32 v8, v8, v19
	s_waitcnt lgkmcnt(0)
	v_mul_f32_e32 v13, v13, v16
	v_mul_f32_e32 v9, v9, v16
	v_mul_f32_e32 v16, v14, v17
	v_mul_f32_e32 v14, v10, v17
	v_mul_f32_e32 v11, v11, v18
	v_mul_f32_e32 v28, v12, v19
	v_mul_f32_e32 v17, v15, v18
	v_mul_f32_e32 v15, v24, v8
	v_mul_f32_e32 v12, v20, v8
	v_mul_f32_e32 v18, v25, v9
	v_mul_f32_e32 v10, v21, v9
	v_mul_f32_e32 v19, v26, v14
	v_mul_f32_e32 v9, v22, v14
	v_mul_f32_e32 v29, v27, v11
	v_mul_f32_e32 v8, v23, v11
	v_fma_f32 v15, v20, v28, -v15
	v_fmac_f32_e32 v12, v24, v28
	v_fma_f32 v14, v21, v13, -v18
	v_fmac_f32_e32 v10, v25, v13
	v_fma_f32 v13, v22, v16, -v19
	v_fmac_f32_e32 v9, v26, v16
	v_fma_f32 v11, v23, v17, -v29
	v_fmac_f32_e32 v8, v27, v17
	s_cbranch_vccnz .LBB0_270
	v_mul_f32_e32 v18, 0x3d800000, v15
	v_bfe_u32 v16, v18, 16, 1
	v_mul_f32_e32 v20, 0x3d800000, v12
	v_add3_u32 v19, v18, v16, s47
	v_lshl_add_u64 v[16:17], v[82:83], 0, v[152:153]
	global_store_short_d16_hi v[16:17], v19, off offset:64
	v_bfe_u32 v19, v20, 16, 1
	v_add3_u32 v19, v20, v19, s47
	global_store_short_d16_hi v[16:17], v19, off offset:96
	v_cvt_f32_ubyte0_e32 v19, v211
	v_mul_f32_e32 v19, v137, v19
	v_mul_f32_e32 v19, 0x3fb8aa3b, v19
	v_exp_f32_e32 v21, v19
	v_mul_f32_e32 v19, 0x3d800000, v14
	v_mul_f32_e32 v24, 0x3d800000, v13
	v_mul_f32_e32 v27, 0x3d800000, v11
	v_bfe_u32 v23, v19, 16, 1
	v_bfe_u32 v26, v24, 16, 1
	v_bfe_u32 v29, v27, 16, 1
	v_mul_f32_e32 v22, 0x3d800000, v10
	v_add3_u32 v23, v19, v23, s47
	v_mul_f32_e32 v25, 0x3d800000, v9
	v_add3_u32 v26, v24, v26, s47
	v_mul_f32_e32 v28, 0x3d800000, v8
	v_add3_u32 v29, v27, v29, s47
	global_store_short_d16_hi v[16:17], v23, off offset:576
	v_bfe_u32 v23, v22, 16, 1
	global_store_short_d16_hi v[16:17], v26, off offset:1088
	v_bfe_u32 v26, v25, 16, 1
	global_store_short_d16_hi v[16:17], v29, off offset:1600
	v_bfe_u32 v29, v28, 16, 1
	v_add3_u32 v23, v22, v23, s47
	v_add3_u32 v26, v25, v26, s47
	v_add3_u32 v29, v28, v29, s47
	global_store_short_d16_hi v[16:17], v23, off offset:608
	v_cvt_f32_ubyte0_e32 v23, v210
	global_store_short_d16_hi v[16:17], v26, off offset:1120
	v_cvt_f32_ubyte0_e32 v26, v205
	global_store_short_d16_hi v[16:17], v29, off offset:1632
	v_cvt_f32_ubyte0_e32 v16, v141
	v_mul_f32_e32 v23, v137, v23
	v_mul_f32_e32 v26, v137, v26
	v_mul_f32_e32 v16, v137, v16
	v_mul_f32_e32 v23, 0x3fb8aa3b, v23
	v_mul_f32_e32 v26, 0x3fb8aa3b, v26
	v_mul_f32_e32 v16, 0x3fb8aa3b, v16
	v_exp_f32_e32 v23, v23
	v_exp_f32_e32 v26, v26
	v_exp_f32_e32 v29, v16
	v_mul_f32_e32 v16, v21, v18
	v_mul_f32_e32 v17, v23, v19
	v_mul_f32_e32 v18, v26, v24
	v_mul_f32_e32 v19, v29, v27
	v_or_b32_e32 v128, v140, v65
	v_cvt_pk_bf16_f32 v16, v16, v17
	v_cvt_pk_bf16_f32 v17, v18, v19
	v_and_b32_e32 v128, -16, v128
	v_lshlrev_b64 v[18:19], 8, v[128:129]
	v_lshl_add_u64 v[18:19], s[20:21], 0, v[18:19]
	v_mov_b32_e32 v73, v153
	v_lshl_add_u64 v[18:19], v[18:19], 0, v[252:253]
	global_store_dwordx2 v[18:19], v[16:17], off offset:3072
	v_mul_f32_e32 v16, v21, v20
	v_mul_f32_e32 v17, v23, v22
	v_mul_f32_e32 v18, v26, v25
	v_mul_f32_e32 v19, v29, v28
	v_or_b32_e32 v128, v140, v68
	v_cvt_pk_bf16_f32 v16, v16, v17
	v_cvt_pk_bf16_f32 v17, v18, v19
	v_and_b32_e32 v128, -16, v128
	v_lshlrev_b64 v[18:19], 8, v[128:129]
	v_lshl_add_u64 v[18:19], s[20:21], 0, v[18:19]
	v_lshl_add_u64 v[18:19], v[18:19], 0, v[252:253]
	s_mov_b64 s[0:1], 0
	global_store_dwordx2 v[18:19], v[16:17], off offset:3072

.LBB0_272:
	v_subrev_u32_e32 v11, s8, v78
	v_and_b32_e32 v11, 0x3ff, v11
	ds_read_b32 v11, v11 offset:49152
	s_nop 0
	ds_read2_b32 v[8:9], v255 offset0:113 offset1:114
	ds_read_b32 v10, v255 offset:460
	v_mul_f32_e32 v12, v69, v225
	v_mul_f32_e32 v13, v69, v226
	v_mul_f32_e32 v14, v69, v227
	v_mul_f32_e32 v15, v69, v228
	v_fma_f32 v16, v225, v69, -v12
	v_floor_f32_e32 v12, v12
	v_fma_f32 v17, v226, v69, -v13
	v_floor_f32_e32 v13, v13
	v_fma_f32 v18, v227, v69, -v14
	v_floor_f32_e32 v14, v14
	v_fma_f32 v19, v228, v69, -v15
	v_floor_f32_e32 v15, v15
	v_fma_f32 v12, v69, v225, -v12
	v_fma_f32 v13, v69, v226, -v13
	v_fma_f32 v14, v69, v227, -v14
	v_fma_f32 v15, v69, v228, -v15
	v_add_f32_e32 v12, v16, v12
	v_add_f32_e32 v13, v17, v13
	v_add_f32_e32 v14, v18, v14
	v_add_f32_e32 v15, v19, v15
	v_sin_f32_e32 v16, v12
	v_cos_f32_e32 v12, v12
	v_sin_f32_e32 v17, v13
	v_cos_f32_e32 v13, v13
	v_sin_f32_e32 v18, v14
	v_cos_f32_e32 v14, v14
	v_sin_f32_e32 v19, v15
	v_cos_f32_e32 v15, v15
	s_and_b64 vcc, exec, s[4:5]
	s_mov_b64 s[0:1], -1
	s_waitcnt lgkmcnt(0)
	v_mul_f32_e32 v0, v0, v11
	s_waitcnt lgkmcnt(0)
	v_mul_f32_e32 v5, v5, v8
	v_mul_f32_e32 v1, v1, v8
	v_mul_f32_e32 v8, v6, v9
	v_mul_f32_e32 v6, v2, v9
	v_mul_f32_e32 v3, v3, v10
	v_mul_f32_e32 v20, v4, v11
	v_mul_f32_e32 v9, v7, v10
	v_mul_f32_e32 v7, v16, v0
	v_mul_f32_e32 v4, v12, v0
	v_mul_f32_e32 v10, v17, v1
	v_mul_f32_e32 v2, v13, v1
	v_mul_f32_e32 v11, v18, v6
	v_mul_f32_e32 v1, v14, v6
	v_mul_f32_e32 v21, v19, v3
	v_mul_f32_e32 v0, v15, v3
	v_fma_f32 v7, v12, v20, -v7
	v_fmac_f32_e32 v4, v16, v20
	v_fma_f32 v6, v13, v5, -v10
	v_fmac_f32_e32 v2, v17, v5
	v_fma_f32 v5, v14, v8, -v11
	v_fmac_f32_e32 v1, v18, v8
	v_fma_f32 v3, v15, v9, -v21
	v_fmac_f32_e32 v0, v19, v9
	s_cbranch_vccnz .LBB0_274
	v_mul_f32_e32 v10, 0x3d800000, v7
	v_bfe_u32 v8, v10, 16, 1
	v_mul_f32_e32 v12, 0x3d800000, v4
	v_add3_u32 v11, v10, v8, s47
	v_lshl_add_u64 v[8:9], v[74:75], 0, v[152:153]
	global_store_short_d16_hi v[8:9], v11, off offset:64
	v_bfe_u32 v11, v12, 16, 1
	v_add3_u32 v11, v12, v11, s47
	global_store_short_d16_hi v[8:9], v11, off offset:96
	v_cvt_f32_ubyte0_e32 v11, v217
	v_mul_f32_e32 v11, v137, v11
	v_mul_f32_e32 v11, 0x3fb8aa3b, v11
	v_exp_f32_e32 v13, v11
	v_mul_f32_e32 v11, 0x3d800000, v6
	v_mul_f32_e32 v16, 0x3d800000, v5
	v_bfe_u32 v15, v11, 16, 1
	v_bfe_u32 v18, v16, 16, 1
	v_mul_f32_e32 v19, 0x3d800000, v3
	v_mul_f32_e32 v14, 0x3d800000, v2
	v_add3_u32 v15, v11, v15, s47
	v_mul_f32_e32 v17, 0x3d800000, v1
	v_add3_u32 v18, v16, v18, s47
	v_bfe_u32 v21, v19, 16, 1
	global_store_short_d16_hi v[8:9], v15, off offset:576
	v_bfe_u32 v15, v14, 16, 1
	global_store_short_d16_hi v[8:9], v18, off offset:1088
	v_bfe_u32 v18, v17, 16, 1
	v_mul_f32_e32 v20, 0x3d800000, v0
	v_add3_u32 v21, v19, v21, s47
	v_add3_u32 v15, v14, v15, s47
	v_add3_u32 v18, v17, v18, s47
	global_store_short_d16_hi v[8:9], v21, off offset:1600
	v_bfe_u32 v21, v20, 16, 1
	global_store_short_d16_hi v[8:9], v15, off offset:608
	v_cvt_f32_ubyte0_e32 v15, v216
	global_store_short_d16_hi v[8:9], v18, off offset:1120
	v_cvt_f32_ubyte0_e32 v18, v139
	v_add3_u32 v21, v20, v21, s47
	v_mul_f32_e32 v15, v137, v15
	v_mul_f32_e32 v18, v137, v18
	global_store_short_d16_hi v[8:9], v21, off offset:1632
	v_mul_f32_e32 v8, v137, v138
	v_mul_f32_e32 v15, 0x3fb8aa3b, v15
	v_mul_f32_e32 v18, 0x3fb8aa3b, v18
	v_mul_f32_e32 v8, 0x3fb8aa3b, v8
	v_exp_f32_e32 v15, v15
	v_exp_f32_e32 v18, v18
	v_exp_f32_e32 v21, v8
	v_mul_f32_e32 v8, v13, v10
	v_mul_f32_e32 v9, v15, v11
	v_mul_f32_e32 v10, v18, v16
	v_mul_f32_e32 v11, v21, v19
	v_or_b32_e32 v128, v136, v65
	v_cvt_pk_bf16_f32 v8, v8, v9
	v_cvt_pk_bf16_f32 v9, v10, v11
	v_and_b32_e32 v128, -16, v128
	v_lshlrev_b64 v[10:11], 8, v[128:129]
	v_lshl_add_u64 v[10:11], s[20:21], 0, v[10:11]
	v_mov_b32_e32 v65, v153
	v_lshl_add_u64 v[10:11], v[10:11], 0, v[252:253]
	global_store_dwordx2 v[10:11], v[8:9], off offset:3584
	v_mul_f32_e32 v8, v13, v12
	v_mul_f32_e32 v9, v15, v14
	v_mul_f32_e32 v10, v18, v17
	v_mul_f32_e32 v11, v21, v20
	v_or_b32_e32 v128, v136, v68
	v_cvt_pk_bf16_f32 v8, v8, v9
	v_cvt_pk_bf16_f32 v9, v10, v11
	v_and_b32_e32 v128, -16, v128
	v_lshlrev_b64 v[10:11], 8, v[128:129]
	v_lshl_add_u64 v[10:11], s[20:21], 0, v[10:11]
	v_lshl_add_u64 v[10:11], v[10:11], 0, v[252:253]
	s_mov_b64 s[0:1], 0
	global_store_dwordx2 v[10:11], v[8:9], off offset:3584
